# GEMM 2x2 mainloops: register double-buffered global prefetch distance 2 + pipelined LDS frag reads; gatherU MFMA chains batched; attention skips window-mask VALU on unmasked tiles
# speedup vs baseline: 1.0173x; 1.0173x over previous
.LBB0_237:
	s_and_b32 s44, s77, 0xffff
	s_mul_i32 s44, s44, 0xaaab
	s_lshr_b32 s45, s44, 19
	s_lshr_b32 s44, s44, 9
	s_mul_i32 s45, s45, 12
	s_and_b32 s72, s44, 0xfc00
	v_readlane_b32 s44, v253, 25
	s_sub_i32 s45, s77, s45
	s_or_b32 s46, s44, s72
	s_and_b32 s62, s45, 0xffff
	s_lshl_b32 s44, s46, 11
	s_add_u32 s48, s2, s44
	s_addc_u32 s49, s3, 0
	s_lshl_b32 s80, s45, 17
	v_mov_b32_e32 v48, v133
	s_lshl_b64 s[44:45], s[80:81], 1
	s_add_u32 s64, s31, s44
	v_add_u32_e32 v8, 0x100, v48
	v_add_u32_e32 v16, 0x200, v48
	v_add_u32_e32 v28, 0x300, v48
	v_lshlrev_b32_e32 v0, 4, v48
	v_ashrrev_i32_e32 v32, 3, v48
	v_ashrrev_i32_e32 v36, 3, v8
	v_ashrrev_i32_e32 v40, 3, v16
	v_ashrrev_i32_e32 v44, 3, v28
	s_addc_u32 s65, s38, s45
	v_and_b32_e32 v128, 0x70, v0
	v_ashrrev_i32_e32 v33, 31, v32
	v_ashrrev_i32_e32 v37, 31, v36
	v_ashrrev_i32_e32 v41, 31, v40
	v_ashrrev_i32_e32 v45, 31, v44
	v_lshl_add_u64 v[24:25], s[48:49], 0, v[128:129]
	v_lshl_add_u64 v[26:27], s[64:65], 0, v[128:129]
	v_lshlrev_b64 v[34:35], 11, v[32:33]
	v_lshlrev_b64 v[38:39], 11, v[36:37]
	v_lshlrev_b64 v[42:43], 11, v[40:41]
	v_lshlrev_b64 v[46:47], 11, v[44:45]
	v_lshl_add_u64 v[0:1], v[24:25], 0, v[34:35]
	v_lshl_add_u64 v[4:5], v[26:27], 0, v[34:35]
	v_lshl_add_u64 v[8:9], v[24:25], 0, v[38:39]
	v_lshl_add_u64 v[12:13], v[26:27], 0, v[38:39]
	v_lshl_add_u64 v[16:17], v[24:25], 0, v[42:43]
	v_lshl_add_u64 v[20:21], v[26:27], 0, v[42:43]
	v_lshl_add_u64 v[24:25], v[24:25], 0, v[46:47]
	v_lshl_add_u64 v[28:29], v[26:27], 0, v[46:47]
	global_load_dwordx4 v[0:3], v[0:1], off
	s_nop 0
	global_load_dwordx4 v[4:7], v[4:5], off
	s_nop 0
	global_load_dwordx4 v[8:11], v[8:9], off
	s_nop 0
	global_load_dwordx4 v[12:15], v[12:13], off
	s_nop 0
	global_load_dwordx4 v[16:19], v[16:17], off
	s_nop 0
	global_load_dwordx4 v[20:23], v[20:21], off
	s_nop 0
	global_load_dwordx4 v[24:27], v[24:25], off
	s_nop 0
	global_load_dwordx4 v[28:31], v[28:29], off
	s_lshl_b32 s47, s72, 11
	s_or_b32 s47, s1, s47
	s_add_u32 s48, s39, s47
	v_and_b32_e32 v33, 31, v48
	v_lshrrev_b32_e32 v37, 1, v48
	v_mul_lo_u32 v84, v32, s85
	s_addc_u32 s49, s74, 0
	v_or_b32_e32 v32, v33, v81
	v_and_b32_e32 v83, 16, v37
	v_or_b32_e32 v33, v33, v80
	v_add_u32_e32 v37, v128, v84
	v_mul_lo_u32 v85, v36, s85
	v_mul_lo_u32 v86, v40, s85
	s_waitcnt vmcnt(9)
	v_mul_lo_u32 v89, v44, s85
	s_add_u32 s44, s75, s44
	v_mul_lo_u32 v87, v32, s85
	v_mul_u32_u24_e32 v88, 0x90, v33
	v_add_u32_e32 v32, v128, v85
	v_add_u32_e32 v33, v128, v86
	v_add_u32_e32 v36, v128, v89
	v_or_b32_e32 v34, v34, v128
	v_or_b32_e32 v38, v38, v128
	v_or_b32_e32 v42, v42, v128
	v_or_b32_e32 v46, v46, v128
	s_addc_u32 s45, s76, s45
	v_lshl_add_u64 v[64:65], s[48:49], 0, v[34:35]
	v_lshl_add_u64 v[66:67], s[48:49], 0, v[38:39]
	v_lshl_add_u64 v[68:69], s[48:49], 0, v[42:43]
	v_lshl_add_u64 v[70:71], s[48:49], 0, v[46:47]
	v_lshl_add_u64 v[72:73], s[44:45], 0, v[34:35]
	v_lshl_add_u64 v[74:75], s[44:45], 0, v[38:39]
	v_lshl_add_u64 v[76:77], s[44:45], 0, v[42:43]
	v_lshl_add_u64 v[78:79], s[44:45], 0, v[46:47]
	s_mov_b32 s47, 0
	s_mov_b64 s[44:45], 0
	global_load_dwordx4 v[192:195], v[64:65], off
	global_load_dwordx4 v[196:199], v[72:73], off
	global_load_dwordx4 v[200:203], v[66:67], off
	global_load_dwordx4 v[204:207], v[74:75], off
	global_load_dwordx4 v[208:211], v[68:69], off
	global_load_dwordx4 v[212:215], v[76:77], off
	global_load_dwordx4 v[216:219], v[70:71], off
	global_load_dwordx4 v[220:223], v[78:79], off
	s_waitcnt vmcnt(15)
	ds_write_b128 v37, v[0:3]
	s_waitcnt vmcnt(14)
	ds_write_b128 v37, v[4:7] offset:36864
	s_waitcnt vmcnt(13)
	ds_write_b128 v32, v[8:11]
	s_waitcnt vmcnt(12)
	ds_write_b128 v32, v[12:15] offset:36864
	s_waitcnt vmcnt(11)
	ds_write_b128 v33, v[16:19]
	s_waitcnt vmcnt(10)
	ds_write_b128 v33, v[20:23] offset:36864
	s_waitcnt vmcnt(9)
	ds_write_b128 v36, v[24:27]
	s_waitcnt vmcnt(8)
	ds_write_b128 v36, v[28:31] offset:36864
	v_mov_b32_e32 v0, 0
	v_mov_b32_e32 v1, v0
	v_mov_b32_e32 v2, v0
	v_mov_b32_e32 v3, v0
	v_mov_b32_e32 v4, v0
	v_mov_b32_e32 v5, v0
	v_mov_b32_e32 v6, v0
	v_mov_b32_e32 v7, v0
	v_mov_b32_e32 v8, v0
	v_mov_b32_e32 v9, v0
	v_mov_b32_e32 v10, v0
	v_mov_b32_e32 v11, v0
	v_mov_b32_e32 v12, v0
	v_mov_b32_e32 v13, v0
	v_mov_b32_e32 v14, v0
	v_mov_b32_e32 v15, v0
	v_mov_b32_e32 v32, v0
	v_mov_b32_e32 v33, v0
	v_mov_b32_e32 v34, v0
	v_mov_b32_e32 v35, v0
	v_mov_b32_e32 v36, v0
	v_mov_b32_e32 v37, v0
	v_mov_b32_e32 v38, v0
	v_mov_b32_e32 v39, v0
	v_mov_b32_e32 v40, v0
	v_mov_b32_e32 v41, v0
	v_mov_b32_e32 v42, v0
	v_mov_b32_e32 v43, v0
	v_mov_b32_e32 v44, v0
	v_mov_b32_e32 v45, v0
	v_mov_b32_e32 v46, v0
	v_mov_b32_e32 v47, v0
	v_mov_b32_e32 v16, v0
	v_mov_b32_e32 v17, v0
	v_mov_b32_e32 v18, v0
	v_mov_b32_e32 v19, v0
	v_mov_b32_e32 v20, v0
	v_mov_b32_e32 v21, v0
	v_mov_b32_e32 v22, v0
	v_mov_b32_e32 v23, v0
	v_mov_b32_e32 v24, v0
	v_mov_b32_e32 v25, v0
	v_mov_b32_e32 v26, v0
	v_mov_b32_e32 v27, v0
	v_mov_b32_e32 v28, v0
	v_mov_b32_e32 v29, v0
	v_mov_b32_e32 v30, v0
	v_mov_b32_e32 v31, v0
	v_mov_b32_e32 v48, v0
	v_mov_b32_e32 v49, v0
	v_mov_b32_e32 v50, v0
	v_mov_b32_e32 v51, v0
	v_mov_b32_e32 v52, v0
	v_mov_b32_e32 v53, v0
	v_mov_b32_e32 v54, v0
	v_mov_b32_e32 v55, v0
	v_mov_b32_e32 v56, v0
	v_mov_b32_e32 v57, v0
	v_mov_b32_e32 v58, v0
	v_mov_b32_e32 v59, v0
	v_mov_b32_e32 v60, v0
	v_mov_b32_e32 v61, v0
	v_mov_b32_e32 v62, v0
	v_mov_b32_e32 v63, v0
	s_waitcnt lgkmcnt(0)
	s_barrier
	v_add_u32_e32 v240, v87, v83
	v_add_u32_e32 v241, v88, v83
	v_add_u32_e32 v242, v128, v84
	v_add_u32_e32 v243, v128, v85
	v_add_u32_e32 v244, v128, v86
	v_add_u32_e32 v245, v128, v89
.Lmm_qkv_loop:
	ds_read_b128 v[90:93], v240
	ds_read_b128 v[94:97], v241 offset:36864
	ds_read_b128 v[98:101], v241 offset:41472
	ds_read_b128 v[102:105], v240 offset:4608
	v_lshl_add_u64 v[224:225], v[64:65], 0, s[44:45]
	v_lshl_add_u64 v[226:227], v[72:73], 0, s[44:45]
	v_lshl_add_u64 v[228:229], v[66:67], 0, s[44:45]
	v_lshl_add_u64 v[230:231], v[74:75], 0, s[44:45]
	v_lshl_add_u64 v[232:233], v[68:69], 0, s[44:45]
	v_lshl_add_u64 v[234:235], v[76:77], 0, s[44:45]
	v_lshl_add_u64 v[236:237], v[70:71], 0, s[44:45]
	v_lshl_add_u64 v[238:239], v[78:79], 0, s[44:45]
	global_load_dwordx4 v[142:145], v[224:225], off offset:128
	global_load_dwordx4 v[146:149], v[226:227], off offset:128
	global_load_dwordx4 v[150:153], v[228:229], off offset:128
	global_load_dwordx4 v[154:157], v[230:231], off offset:128
	global_load_dwordx4 v[158:161], v[232:233], off offset:128
	global_load_dwordx4 v[162:165], v[234:235], off offset:128
	global_load_dwordx4 v[166:169], v[236:237], off offset:128
	global_load_dwordx4 v[170:173], v[238:239], off offset:128
	ds_read_b128 v[106:109], v240 offset:32
	ds_read_b128 v[110:113], v241 offset:36896
	ds_read_b128 v[114:117], v241 offset:41504
	ds_read_b128 v[118:121], v240 offset:4640
	s_waitcnt lgkmcnt(4)
	v_mfma_f32_32x32x16_bf16 v[0:15], v[90:93], v[94:97], v[0:15]
	v_mfma_f32_32x32x16_bf16 v[32:47], v[90:93], v[98:101], v[32:47]
	v_mfma_f32_32x32x16_bf16 v[16:31], v[102:105], v[94:97], v[16:31]
	v_mfma_f32_32x32x16_bf16 v[48:63], v[102:105], v[98:101], v[48:63]
	ds_read_b128 v[90:93], v240 offset:64
	ds_read_b128 v[94:97], v241 offset:36928
	ds_read_b128 v[98:101], v241 offset:41536
	ds_read_b128 v[102:105], v240 offset:4672
	s_waitcnt lgkmcnt(4)
	v_mfma_f32_32x32x16_bf16 v[0:15], v[106:109], v[110:113], v[0:15]
	v_mfma_f32_32x32x16_bf16 v[32:47], v[106:109], v[114:117], v[32:47]
	v_mfma_f32_32x32x16_bf16 v[16:31], v[118:121], v[110:113], v[16:31]
	v_mfma_f32_32x32x16_bf16 v[48:63], v[118:121], v[114:117], v[48:63]
	ds_read_b128 v[106:109], v240 offset:96
	ds_read_b128 v[110:113], v241 offset:36960
	ds_read_b128 v[114:117], v241 offset:41568
	ds_read_b128 v[118:121], v240 offset:4704
	s_waitcnt lgkmcnt(4)
	v_mfma_f32_32x32x16_bf16 v[0:15], v[90:93], v[94:97], v[0:15]
	v_mfma_f32_32x32x16_bf16 v[32:47], v[90:93], v[98:101], v[32:47]
	v_mfma_f32_32x32x16_bf16 v[16:31], v[102:105], v[94:97], v[16:31]
	v_mfma_f32_32x32x16_bf16 v[48:63], v[102:105], v[98:101], v[48:63]
	s_add_u32 s44, s44, 0x80
	s_addc_u32 s45, s45, 0
	s_waitcnt vmcnt(8)
	ds_write_b128 v242, v[192:195] offset:18432
	ds_write_b128 v242, v[196:199] offset:55296
	ds_write_b128 v243, v[200:203] offset:18432
	ds_write_b128 v243, v[204:207] offset:55296
	s_waitcnt lgkmcnt(4)
	v_mfma_f32_32x32x16_bf16 v[0:15], v[106:109], v[110:113], v[0:15]
	v_mfma_f32_32x32x16_bf16 v[32:47], v[106:109], v[114:117], v[32:47]
	ds_write_b128 v244, v[208:211] offset:18432
	ds_write_b128 v244, v[212:215] offset:55296
	ds_write_b128 v245, v[216:219] offset:18432
	ds_write_b128 v245, v[220:223] offset:55296
	v_mfma_f32_32x32x16_bf16 v[16:31], v[118:121], v[110:113], v[16:31]
	v_mfma_f32_32x32x16_bf16 v[48:63], v[118:121], v[114:117], v[48:63]
	s_waitcnt lgkmcnt(0)
	s_barrier
	ds_read_b128 v[90:93], v240 offset:18432
	ds_read_b128 v[94:97], v241 offset:55296
	ds_read_b128 v[98:101], v241 offset:59904
	ds_read_b128 v[102:105], v240 offset:23040
	v_lshl_add_u64 v[224:225], v[64:65], 0, s[44:45]
	v_lshl_add_u64 v[226:227], v[72:73], 0, s[44:45]
	v_lshl_add_u64 v[228:229], v[66:67], 0, s[44:45]
	v_lshl_add_u64 v[230:231], v[74:75], 0, s[44:45]
	v_lshl_add_u64 v[232:233], v[68:69], 0, s[44:45]
	v_lshl_add_u64 v[234:235], v[76:77], 0, s[44:45]
	v_lshl_add_u64 v[236:237], v[70:71], 0, s[44:45]
	v_lshl_add_u64 v[238:239], v[78:79], 0, s[44:45]
	global_load_dwordx4 v[192:195], v[224:225], off offset:128
	global_load_dwordx4 v[196:199], v[226:227], off offset:128
	global_load_dwordx4 v[200:203], v[228:229], off offset:128
	global_load_dwordx4 v[204:207], v[230:231], off offset:128
	global_load_dwordx4 v[208:211], v[232:233], off offset:128
	global_load_dwordx4 v[212:215], v[234:235], off offset:128
	global_load_dwordx4 v[216:219], v[236:237], off offset:128
	global_load_dwordx4 v[220:223], v[238:239], off offset:128
	ds_read_b128 v[106:109], v240 offset:18464
	ds_read_b128 v[110:113], v241 offset:55328
	ds_read_b128 v[114:117], v241 offset:59936
	ds_read_b128 v[118:121], v240 offset:23072
	s_waitcnt lgkmcnt(4)
	v_mfma_f32_32x32x16_bf16 v[0:15], v[90:93], v[94:97], v[0:15]
	v_mfma_f32_32x32x16_bf16 v[32:47], v[90:93], v[98:101], v[32:47]
	v_mfma_f32_32x32x16_bf16 v[16:31], v[102:105], v[94:97], v[16:31]
	v_mfma_f32_32x32x16_bf16 v[48:63], v[102:105], v[98:101], v[48:63]
	ds_read_b128 v[90:93], v240 offset:18496
	ds_read_b128 v[94:97], v241 offset:55360
	ds_read_b128 v[98:101], v241 offset:59968
	ds_read_b128 v[102:105], v240 offset:23104
	s_waitcnt lgkmcnt(4)
	v_mfma_f32_32x32x16_bf16 v[0:15], v[106:109], v[110:113], v[0:15]
	v_mfma_f32_32x32x16_bf16 v[32:47], v[106:109], v[114:117], v[32:47]
	v_mfma_f32_32x32x16_bf16 v[16:31], v[118:121], v[110:113], v[16:31]
	v_mfma_f32_32x32x16_bf16 v[48:63], v[118:121], v[114:117], v[48:63]
	ds_read_b128 v[106:109], v240 offset:18528
	ds_read_b128 v[110:113], v241 offset:55392
	ds_read_b128 v[114:117], v241 offset:60000
	ds_read_b128 v[118:121], v240 offset:23136
	s_waitcnt lgkmcnt(4)
	v_mfma_f32_32x32x16_bf16 v[0:15], v[90:93], v[94:97], v[0:15]
	v_mfma_f32_32x32x16_bf16 v[32:47], v[90:93], v[98:101], v[32:47]
	v_mfma_f32_32x32x16_bf16 v[16:31], v[102:105], v[94:97], v[16:31]
	v_mfma_f32_32x32x16_bf16 v[48:63], v[102:105], v[98:101], v[48:63]
	s_add_u32 s44, s44, 0x80
	s_addc_u32 s45, s45, 0
	s_waitcnt vmcnt(8)
	ds_write_b128 v242, v[142:145]
	ds_write_b128 v242, v[146:149] offset:36864
	ds_write_b128 v243, v[150:153]
	ds_write_b128 v243, v[154:157] offset:36864
	s_waitcnt lgkmcnt(4)
	v_mfma_f32_32x32x16_bf16 v[0:15], v[106:109], v[110:113], v[0:15]
	v_mfma_f32_32x32x16_bf16 v[32:47], v[106:109], v[114:117], v[32:47]
	ds_write_b128 v244, v[158:161]
	ds_write_b128 v244, v[162:165] offset:36864
	ds_write_b128 v245, v[166:169]
	ds_write_b128 v245, v[170:173] offset:36864
	v_mfma_f32_32x32x16_bf16 v[16:31], v[118:121], v[110:113], v[16:31]
	v_mfma_f32_32x32x16_bf16 v[48:63], v[118:121], v[114:117], v[48:63]
	s_waitcnt lgkmcnt(0)
	s_barrier
	s_cmpk_lg_i32 s44, 0x700
	s_cbranch_scc1 .Lmm_qkv_loop
	ds_read_b128 v[90:93], v240
	ds_read_b128 v[94:97], v241 offset:36864
	ds_read_b128 v[98:101], v241 offset:41472
	ds_read_b128 v[102:105], v240 offset:4608
	ds_read_b128 v[106:109], v240 offset:32
	ds_read_b128 v[110:113], v241 offset:36896
	ds_read_b128 v[114:117], v241 offset:41504
	ds_read_b128 v[118:121], v240 offset:4640
	s_waitcnt lgkmcnt(4)
	v_mfma_f32_32x32x16_bf16 v[0:15], v[90:93], v[94:97], v[0:15]
	v_mfma_f32_32x32x16_bf16 v[32:47], v[90:93], v[98:101], v[32:47]
	v_mfma_f32_32x32x16_bf16 v[16:31], v[102:105], v[94:97], v[16:31]
	v_mfma_f32_32x32x16_bf16 v[48:63], v[102:105], v[98:101], v[48:63]
	ds_read_b128 v[90:93], v240 offset:64
	ds_read_b128 v[94:97], v241 offset:36928
	ds_read_b128 v[98:101], v241 offset:41536
	ds_read_b128 v[102:105], v240 offset:4672
	s_waitcnt lgkmcnt(4)
	v_mfma_f32_32x32x16_bf16 v[0:15], v[106:109], v[110:113], v[0:15]
	v_mfma_f32_32x32x16_bf16 v[32:47], v[106:109], v[114:117], v[32:47]
	v_mfma_f32_32x32x16_bf16 v[16:31], v[118:121], v[110:113], v[16:31]
	v_mfma_f32_32x32x16_bf16 v[48:63], v[118:121], v[114:117], v[48:63]
	ds_read_b128 v[106:109], v240 offset:96
	ds_read_b128 v[110:113], v241 offset:36960
	ds_read_b128 v[114:117], v241 offset:41568
	ds_read_b128 v[118:121], v240 offset:4704
	s_waitcnt lgkmcnt(4)
	v_mfma_f32_32x32x16_bf16 v[0:15], v[90:93], v[94:97], v[0:15]
	v_mfma_f32_32x32x16_bf16 v[32:47], v[90:93], v[98:101], v[32:47]
	v_mfma_f32_32x32x16_bf16 v[16:31], v[102:105], v[94:97], v[16:31]
	v_mfma_f32_32x32x16_bf16 v[48:63], v[102:105], v[98:101], v[48:63]
	s_waitcnt vmcnt(0)
	ds_write_b128 v242, v[192:195] offset:18432
	ds_write_b128 v242, v[196:199] offset:55296
	ds_write_b128 v243, v[200:203] offset:18432
	ds_write_b128 v243, v[204:207] offset:55296
	s_waitcnt lgkmcnt(4)
	v_mfma_f32_32x32x16_bf16 v[0:15], v[106:109], v[110:113], v[0:15]
	v_mfma_f32_32x32x16_bf16 v[32:47], v[106:109], v[114:117], v[32:47]
	ds_write_b128 v244, v[208:211] offset:18432
	ds_write_b128 v244, v[212:215] offset:55296
	ds_write_b128 v245, v[216:219] offset:18432
	ds_write_b128 v245, v[220:223] offset:55296
	v_mfma_f32_32x32x16_bf16 v[16:31], v[118:121], v[110:113], v[16:31]
	v_mfma_f32_32x32x16_bf16 v[48:63], v[118:121], v[114:117], v[48:63]
	s_waitcnt lgkmcnt(0)
	s_barrier
	ds_read_b128 v[90:93], v240 offset:18432
	ds_read_b128 v[94:97], v241 offset:55296
	ds_read_b128 v[98:101], v241 offset:59904
	ds_read_b128 v[102:105], v240 offset:23040
	ds_read_b128 v[106:109], v240 offset:18464
	ds_read_b128 v[110:113], v241 offset:55328
	ds_read_b128 v[114:117], v241 offset:59936
	ds_read_b128 v[118:121], v240 offset:23072
	s_waitcnt lgkmcnt(4)
	v_mfma_f32_32x32x16_bf16 v[0:15], v[90:93], v[94:97], v[0:15]
	v_mfma_f32_32x32x16_bf16 v[32:47], v[90:93], v[98:101], v[32:47]
	v_mfma_f32_32x32x16_bf16 v[16:31], v[102:105], v[94:97], v[16:31]
	v_mfma_f32_32x32x16_bf16 v[48:63], v[102:105], v[98:101], v[48:63]
	ds_read_b128 v[90:93], v240 offset:18496
	ds_read_b128 v[94:97], v241 offset:55360
	ds_read_b128 v[98:101], v241 offset:59968
	ds_read_b128 v[102:105], v240 offset:23104
	s_waitcnt lgkmcnt(4)
	v_mfma_f32_32x32x16_bf16 v[0:15], v[106:109], v[110:113], v[0:15]
	v_mfma_f32_32x32x16_bf16 v[32:47], v[106:109], v[114:117], v[32:47]
	v_mfma_f32_32x32x16_bf16 v[16:31], v[118:121], v[110:113], v[16:31]
	v_mfma_f32_32x32x16_bf16 v[48:63], v[118:121], v[114:117], v[48:63]
	ds_read_b128 v[106:109], v240 offset:18528
	ds_read_b128 v[110:113], v241 offset:55392
	ds_read_b128 v[114:117], v241 offset:60000
	ds_read_b128 v[118:121], v240 offset:23136
	s_waitcnt lgkmcnt(4)
	v_mfma_f32_32x32x16_bf16 v[0:15], v[90:93], v[94:97], v[0:15]
	v_mfma_f32_32x32x16_bf16 v[32:47], v[90:93], v[98:101], v[32:47]
	v_mfma_f32_32x32x16_bf16 v[16:31], v[102:105], v[94:97], v[16:31]
	v_mfma_f32_32x32x16_bf16 v[48:63], v[102:105], v[98:101], v[48:63]
	s_waitcnt lgkmcnt(0)
	s_barrier
	v_mfma_f32_32x32x16_bf16 v[0:15], v[106:109], v[110:113], v[0:15]
	v_mfma_f32_32x32x16_bf16 v[32:47], v[106:109], v[114:117], v[32:47]
	v_mfma_f32_32x32x16_bf16 v[16:31], v[118:121], v[110:113], v[16:31]
	v_mfma_f32_32x32x16_bf16 v[48:63], v[118:121], v[114:117], v[48:63]
	s_nop 15
	s_movk_i32 s44, 0x2000
	s_and_b32 s66, s62, 0xffff
	s_cmp_gt_u32 s66, 9
	s_mov_b32 s78, 0
	v_add_u32_e32 v64, s46, v81
	v_cmp_gt_i32_e64 s[44:45], s44, v64
	v_mov_b32_e32 v64, v133
	v_mov_b32_e32 v66, v133
	v_lshl_or_b32 v65, s62, 7, v80
	v_lshrrev_b32_e32 v66, 6, v66
	v_and_b32_e32 v67, 31, v64
	v_mul_lo_u32 v66, v66, s6
	v_lshl_or_b32 v67, v67, 2, v66
	s_cselect_b64 s[62:63], -1, 0
	s_or_b64 s[64:65], s[44:45], s[62:63]
	s_cmp_gt_u32 s66, 7
	s_cselect_b64 s[66:67], -1, 0
	v_lshrrev_b32_e32 v68, 3, v64
	v_and_b32_e32 v68, 4, v68
	v_mad_u32_u24 v67, v68, s7, v67
	ds_write2_b32 v67, v0, v32 offset1:32
	ds_write2_b32 v67, v1, v33 offset0:68 offset1:100
	ds_write2_b32 v67, v2, v34 offset0:136 offset1:168
	ds_write2_b32 v67, v3, v35 offset0:204 offset1:236
	v_add_u32_e32 v0, 0x800, v67
	ds_write2_b32 v0, v4, v36 offset0:32 offset1:64
	ds_write2_b32 v0, v5, v37 offset0:100 offset1:132
	ds_write2_b32 v0, v6, v38 offset0:168 offset1:200
	v_add_u32_e32 v0, 0xa00, v67
	ds_write2_b32 v0, v7, v39 offset0:108 offset1:140
	v_add_u32_e32 v0, 0x1000, v67
	ds_write2_b32 v0, v8, v40 offset0:64 offset1:96
	ds_write2_b32 v0, v9, v41 offset0:132 offset1:164
	ds_write2_b32 v0, v10, v42 offset0:200 offset1:232
	v_add_u32_e32 v0, 0x1400, v67
	ds_write2_b32 v0, v11, v43 offset0:12 offset1:44
	v_add_u32_e32 v0, 0x1800, v67
	ds_write2_b32 v0, v12, v44 offset0:96 offset1:128
	ds_write2_b32 v0, v13, v45 offset0:164 offset1:196
	v_add_u32_e32 v0, 0x1a00, v67
	ds_write2_b32 v0, v14, v46 offset0:104 offset1:136
	v_add_u32_e32 v0, 0x1c00, v67
	ds_write2_b32 v0, v15, v47 offset0:44 offset1:76
	v_add_u32_e32 v0, 0x2000, v67
	ds_write2_b32 v0, v16, v48 offset0:128 offset1:160
	ds_write2_b32 v0, v17, v49 offset0:196 offset1:228
	v_add_u32_e32 v0, 0x2400, v67
	ds_write2_b32 v0, v18, v50 offset0:8 offset1:40
	ds_write2_b32 v0, v19, v51 offset0:76 offset1:108
	v_add_u32_e32 v0, 0x2800, v67
	ds_write2_b32 v0, v20, v52 offset0:160 offset1:192
	v_add_u32_e32 v0, 0x2a00, v67
	ds_write2_b32 v0, v21, v53 offset0:100 offset1:132
	v_add_u32_e32 v0, 0x2c00, v67
	ds_write2_b32 v0, v22, v54 offset0:40 offset1:72
	ds_write2_b32 v0, v23, v55 offset0:108 offset1:140
	v_add_u32_e32 v0, 0x3000, v67
	ds_write2_b32 v0, v24, v56 offset0:192 offset1:224
	v_add_u32_e32 v0, 0x3400, v67
	ds_write2_b32 v0, v25, v57 offset0:4 offset1:36
	ds_write2_b32 v0, v26, v58 offset0:72 offset1:104
	ds_write2_b32 v0, v27, v59 offset0:140 offset1:172
	v_add_u32_e32 v0, 0x3a00, v67
	ds_write2_b32 v0, v28, v60 offset0:96 offset1:128
	v_add_u32_e32 v0, 0x3c00, v67
	ds_write2_b32 v0, v29, v61 offset0:36 offset1:68
	ds_write2_b32 v0, v30, v62 offset0:104 offset1:136
	ds_write2_b32 v0, v31, v63 offset0:172 offset1:204
	v_lshlrev_b32_e32 v0, 3, v64
	v_and_b32_e32 v12, 56, v0
	v_and_b32_e32 v0, 2, v64
	v_cmp_eq_u32_e64 s[48:49], 0, v0
	v_lshlrev_b32_e32 v0, 5, v64
	v_and_b32_e32 v128, 32, v0
	v_lshlrev_b32_e32 v0, 1, v65
	v_mov_b32_e32 v1, v129
	v_lshlrev_b32_e32 v2, 2, v65
	v_mov_b32_e32 v3, v129
	v_lshl_add_u64 v[16:17], s[54:55], 0, v[0:1]
	v_lshl_add_u64 v[18:19], s[52:53], 0, v[2:3]
	v_lshl_add_u64 v[0:1], s[50:51], 0, v[0:1]
	v_lshlrev_b32_e32 v2, 1, v12
	v_bfe_u32 v4, v64, 3, 3
	v_lshl_add_u64 v[20:21], v[0:1], 0, v[2:3]
	v_and_b32_e32 v1, 7, v64
	v_mul_u32_u24_e32 v0, 0x110, v4
	v_lshlrev_b32_e32 v1, 5, v1
	v_cmp_gt_u32_e64 s[46:47], 32, v12
	v_cndmask_b32_e64 v13, v187, 64, s[48:49]
	v_lshl_add_u64 v[14:15], s[56:57], 0, v[128:129]
	v_lshl_add_u64 v[22:23], s[58:59], 0, v[128:129]
	v_add3_u32 v28, v82, s72, v4
	v_add3_u32 v29, v66, v0, v1
	s_branch .LBB0_241

.LBB0_379:
	v_add_u32_e32 v122, v108, v110
	ds_read_b128 v[32:35], v122
	ds_read_b128 v[36:39], v122 offset:32
	v_add_u32_e32 v127, s95, v97
	v_cmp_gt_u32_e32 vcc, s9, v127
	s_waitcnt lgkmcnt(1)
	v_mfma_f32_32x32x16_bf16 v[48:63], v[32:35], v[72:75], 0
	ds_read_b128 v[32:35], v122 offset:64
	ds_read_b128 v[118:121], v122 offset:4640
	s_waitcnt lgkmcnt(2)
	v_mfma_f32_32x32x16_bf16 v[48:63], v[36:39], v[76:79], v[48:63]
	s_waitcnt lgkmcnt(1)
	v_mfma_f32_32x32x16_bf16 v[48:63], v[32:35], v[84:87], v[48:63]
	ds_read_b128 v[32:35], v122 offset:96
	s_waitcnt lgkmcnt(0)
	v_mfma_f32_32x32x16_bf16 v[48:63], v[32:35], v[92:95], v[48:63]
	ds_read_b128 v[32:35], v122 offset:4608
	s_waitcnt lgkmcnt(0)
	v_mfma_f32_32x32x16_bf16 v[32:47], v[32:35], v[72:75], 0
	v_mfma_f32_32x32x16_bf16 v[32:47], v[118:121], v[76:79], v[32:47]
	ds_read_b128 v[118:121], v122 offset:4672
	s_waitcnt lgkmcnt(0)
	v_mfma_f32_32x32x16_bf16 v[32:47], v[118:121], v[84:87], v[32:47]
	ds_read_b128 v[118:121], v122 offset:4704
	s_waitcnt lgkmcnt(0)
	v_mfma_f32_32x32x16_bf16 v[32:47], v[118:121], v[92:95], v[32:47]
	s_cmp_eq_u64 s[64:65], 0
	s_cbranch_scc1 .Lattn_nomask
	s_nop 1
	v_cndmask_b32_e32 v118, v189, v48, vcc
	v_cndmask_b32_e64 v48, v48, v118, s[64:65]
	v_add_u32_e32 v118, 1, v127
	v_cmp_gt_u32_e32 vcc, s9, v118
	s_nop 1
	v_cndmask_b32_e32 v118, v189, v49, vcc
	v_cndmask_b32_e64 v49, v49, v118, s[64:65]
	v_add_u32_e32 v118, 2, v127
	v_cmp_gt_u32_e32 vcc, s9, v118
	v_max3_f32 v119, v117, v48, v49
	s_nop 0
	v_cndmask_b32_e32 v118, v189, v50, vcc
	v_cndmask_b32_e64 v50, v50, v118, s[64:65]
	v_add_u32_e32 v118, 3, v127
	v_cmp_gt_u32_e32 vcc, s9, v118
	s_nop 1
	v_cndmask_b32_e32 v118, v189, v51, vcc
	v_cndmask_b32_e64 v118, v51, v118, s[64:65]
	v_max3_f32 v51, v119, v50, v118
	v_add_u32_e32 v119, 8, v127
	v_cmp_gt_u32_e32 vcc, s9, v119
	s_nop 1
	v_cndmask_b32_e32 v119, v189, v52, vcc
	v_cndmask_b32_e64 v52, v52, v119, s[64:65]
	v_add_u32_e32 v119, 9, v127
	v_cmp_gt_u32_e32 vcc, s9, v119
	s_nop 1
	v_cndmask_b32_e32 v119, v189, v53, vcc
	v_cndmask_b32_e64 v53, v53, v119, s[64:65]
	v_add_u32_e32 v119, 10, v127
	v_cmp_gt_u32_e32 vcc, s9, v119
	v_max3_f32 v51, v51, v52, v53
	s_nop 0
	v_cndmask_b32_e32 v119, v189, v54, vcc
	v_cndmask_b32_e64 v54, v54, v119, s[64:65]
	v_add_u32_e32 v119, 11, v127
	v_cmp_gt_u32_e32 vcc, s9, v119
	s_nop 1
	v_cndmask_b32_e32 v119, v189, v55, vcc
	v_cndmask_b32_e64 v119, v55, v119, s[64:65]
	v_add_u32_e32 v55, 16, v127
	v_cmp_gt_u32_e32 vcc, s9, v55
	v_max3_f32 v51, v51, v54, v119
	s_nop 0
	v_cndmask_b32_e32 v55, v189, v56, vcc
	v_cndmask_b32_e64 v121, v56, v55, s[64:65]
	v_add_u32_e32 v55, 17, v127
	v_cmp_gt_u32_e32 vcc, s9, v55
	s_nop 1
	v_cndmask_b32_e32 v55, v189, v57, vcc
	v_cndmask_b32_e64 v120, v57, v55, s[64:65]
	v_add_u32_e32 v55, 18, v127
	v_cmp_gt_u32_e32 vcc, s9, v55
	v_max3_f32 v51, v51, v121, v120
	s_nop 0
	v_cndmask_b32_e32 v55, v189, v58, vcc
	v_cndmask_b32_e64 v122, v58, v55, s[64:65]
	v_add_u32_e32 v55, 19, v127
	v_cmp_gt_u32_e32 vcc, s9, v55
	s_nop 1
	v_cndmask_b32_e32 v55, v189, v59, vcc
	v_cndmask_b32_e64 v123, v59, v55, s[64:65]
	v_add_u32_e32 v55, 24, v127
	v_cmp_gt_u32_e32 vcc, s9, v55
	v_max3_f32 v51, v51, v122, v123
	s_nop 0
	v_cndmask_b32_e32 v55, v189, v60, vcc
	v_cndmask_b32_e64 v60, v60, v55, s[64:65]
	v_add_u32_e32 v55, 25, v127
	v_cmp_gt_u32_e32 vcc, s9, v55
	s_nop 1
	v_cndmask_b32_e32 v55, v189, v61, vcc
	v_cndmask_b32_e64 v61, v61, v55, s[64:65]
	v_add_u32_e32 v55, 26, v127
	v_cmp_gt_u32_e32 vcc, s9, v55
	v_max3_f32 v51, v51, v60, v61
	s_nop 0
	v_cndmask_b32_e32 v55, v189, v62, vcc
	v_cndmask_b32_e64 v62, v62, v55, s[64:65]
	v_add_u32_e32 v55, 27, v127
	v_cmp_gt_u32_e32 vcc, s9, v55
	s_nop 1
	v_cndmask_b32_e32 v55, v189, v63, vcc
	v_cndmask_b32_e64 v63, v63, v55, s[64:65]
	v_add_u32_e32 v55, 32, v127
	v_cmp_gt_u32_e32 vcc, s9, v55
	v_max3_f32 v51, v51, v62, v63
	s_nop 0
	v_cndmask_b32_e32 v55, v189, v32, vcc
	v_cndmask_b32_e64 v124, v32, v55, s[64:65]
	v_add_u32_e32 v32, 33, v127
	v_cmp_gt_u32_e32 vcc, s9, v32
	s_nop 1
	v_cndmask_b32_e32 v32, v189, v33, vcc
	v_cndmask_b32_e64 v125, v33, v32, s[64:65]
	v_add_u32_e32 v33, 34, v127
	v_cmp_gt_u32_e32 vcc, s9, v33
	v_max3_f32 v32, v51, v124, v125
	s_nop 0
	v_cndmask_b32_e32 v33, v189, v34, vcc
	v_cndmask_b32_e64 v126, v34, v33, s[64:65]
	v_add_u32_e32 v33, 35, v127
	v_cmp_gt_u32_e32 vcc, s9, v33
	v_add_u32_e32 v34, 57, v127
	s_nop 0
	v_cndmask_b32_e32 v33, v189, v35, vcc
	v_cndmask_b32_e64 v59, v35, v33, s[64:65]
	v_add_u32_e32 v33, 40, v127
	v_cmp_gt_u32_e32 vcc, s9, v33
	v_max3_f32 v32, v32, v126, v59
	s_nop 0
	v_cndmask_b32_e32 v33, v189, v36, vcc
	v_cndmask_b32_e64 v56, v36, v33, s[64:65]
	v_add_u32_e32 v33, 41, v127
	v_cmp_gt_u32_e32 vcc, s9, v33
	s_nop 1
	v_cndmask_b32_e32 v33, v189, v37, vcc
	v_cndmask_b32_e64 v57, v37, v33, s[64:65]
	v_add_u32_e32 v33, 42, v127
	v_cmp_gt_u32_e32 vcc, s9, v33
	v_max3_f32 v32, v32, v56, v57
	s_nop 0
	v_cndmask_b32_e32 v33, v189, v38, vcc
	v_cndmask_b32_e64 v58, v38, v33, s[64:65]
	v_add_u32_e32 v33, 43, v127
	v_cmp_gt_u32_e32 vcc, s9, v33
	s_nop 1
	v_cndmask_b32_e32 v33, v189, v39, vcc
	v_cndmask_b32_e64 v55, v39, v33, s[64:65]
	v_add_u32_e32 v33, 48, v127
	v_cmp_gt_u32_e32 vcc, s9, v33
	v_max3_f32 v32, v32, v58, v55
	s_nop 0
	v_cndmask_b32_e32 v33, v189, v40, vcc
	v_cndmask_b32_e64 v37, v40, v33, s[64:65]
	v_add_u32_e32 v33, 49, v127
	v_cmp_gt_u32_e32 vcc, s9, v33
	s_nop 1
	v_cndmask_b32_e32 v33, v189, v41, vcc
	v_cndmask_b32_e64 v38, v41, v33, s[64:65]
	v_add_u32_e32 v33, 50, v127
	v_cmp_gt_u32_e32 vcc, s9, v33
	v_max3_f32 v32, v32, v37, v38
	s_nop 0
	v_cndmask_b32_e32 v33, v189, v42, vcc
	v_cndmask_b32_e64 v39, v42, v33, s[64:65]
	v_add_u32_e32 v33, 51, v127
	v_cmp_gt_u32_e32 vcc, s9, v33
	s_nop 1
	v_cndmask_b32_e32 v33, v189, v43, vcc
	v_cndmask_b32_e64 v36, v43, v33, s[64:65]
	v_add_u32_e32 v33, 56, v127
	v_cmp_gt_u32_e32 vcc, s9, v33
	v_max3_f32 v32, v32, v39, v36
	s_nop 0
	v_cndmask_b32_e32 v33, v189, v44, vcc
	v_cmp_gt_u32_e32 vcc, s9, v34
	v_cndmask_b32_e64 v33, v44, v33, s[64:65]
	s_nop 0
	v_cndmask_b32_e32 v34, v189, v45, vcc
	v_cndmask_b32_e64 v34, v45, v34, s[64:65]
	v_max3_f32 v40, v32, v33, v34
	v_add_u32_e32 v32, 58, v127
	v_cmp_gt_u32_e32 vcc, s9, v32
	s_nop 1
	v_cndmask_b32_e32 v32, v189, v46, vcc
	v_cndmask_b32_e64 v35, v46, v32, s[64:65]
	v_add_u32_e32 v32, 59, v127
	v_cmp_gt_u32_e32 vcc, s9, v32
	s_nop 1
	v_cndmask_b32_e32 v32, v189, v47, vcc
	v_cndmask_b32_e64 v32, v47, v32, s[64:65]
	v_max3_f32 v40, v40, v35, v32
.Lattn_join:
	ds_bpermute_b32 v41, v109, v40
	s_waitcnt lgkmcnt(0)
	v_max_f32_e32 v41, v41, v41
	v_max_f32_e32 v51, v40, v41
	v_cmp_neq_f32_e32 vcc, v51, v117
	s_cbranch_vccz .LBB0_381
	v_sub_f32_e32 v40, v117, v51
	v_exp_f32_e32 v40, v40
	s_nop 0
	v_pk_mul_f32 v[30:31], v[30:31], v[40:41] op_sel_hi:[1,0]
	v_pk_mul_f32 v[28:29], v[28:29], v[40:41] op_sel_hi:[1,0]
	v_pk_mul_f32 v[26:27], v[26:27], v[40:41] op_sel_hi:[1,0]
	v_pk_mul_f32 v[24:25], v[24:25], v[40:41] op_sel_hi:[1,0]
	v_pk_mul_f32 v[22:23], v[22:23], v[40:41] op_sel_hi:[1,0]
	v_pk_mul_f32 v[20:21], v[20:21], v[40:41] op_sel_hi:[1,0]
	v_pk_mul_f32 v[18:19], v[18:19], v[40:41] op_sel_hi:[1,0]
	v_pk_mul_f32 v[16:17], v[16:17], v[40:41] op_sel_hi:[1,0]
	v_pk_mul_f32 v[14:15], v[14:15], v[40:41] op_sel_hi:[1,0]
	v_pk_mul_f32 v[12:13], v[12:13], v[40:41] op_sel_hi:[1,0]
	v_pk_mul_f32 v[10:11], v[10:11], v[40:41] op_sel_hi:[1,0]
	v_pk_mul_f32 v[8:9], v[8:9], v[40:41] op_sel_hi:[1,0]
	v_pk_mul_f32 v[6:7], v[6:7], v[40:41] op_sel_hi:[1,0]
	v_pk_mul_f32 v[4:5], v[4:5], v[40:41] op_sel_hi:[1,0]
	v_pk_mul_f32 v[2:3], v[2:3], v[40:41] op_sel_hi:[1,0]
	v_pk_mul_f32 v[0:1], v[0:1], v[40:41] op_sel_hi:[1,0]
	v_mul_f32_e32 v99, v99, v40

.Lattn_nomask:
	s_nop 3
	v_max3_f32 v119, v117, v48, v49
	v_mov_b32_e32 v118, v51
	v_max3_f32 v51, v119, v50, v118
	v_max3_f32 v51, v51, v52, v53
	v_mov_b32_e32 v119, v55
	v_max3_f32 v51, v51, v54, v119
	v_mov_b32_e32 v121, v56
	v_mov_b32_e32 v120, v57
	v_max3_f32 v51, v51, v121, v120
	v_mov_b32_e32 v122, v58
	v_mov_b32_e32 v123, v59
	v_max3_f32 v51, v51, v122, v123
	v_max3_f32 v51, v51, v60, v61
	v_max3_f32 v51, v51, v62, v63
	v_mov_b32_e32 v124, v32
	v_mov_b32_e32 v125, v33
	v_max3_f32 v32, v51, v124, v125
	v_mov_b32_e32 v126, v34
	v_mov_b32_e32 v59, v35
	v_max3_f32 v32, v32, v126, v59
	v_mov_b32_e32 v56, v36
	v_mov_b32_e32 v57, v37
	v_max3_f32 v32, v32, v56, v57
	v_mov_b32_e32 v58, v38
	v_mov_b32_e32 v55, v39
	v_max3_f32 v32, v32, v58, v55
	v_mov_b32_e32 v37, v40
	v_mov_b32_e32 v38, v41
	v_max3_f32 v32, v32, v37, v38
	v_mov_b32_e32 v39, v42
	v_mov_b32_e32 v36, v43
	v_max3_f32 v32, v32, v39, v36
	v_mov_b32_e32 v33, v44
	v_mov_b32_e32 v34, v45
	v_max3_f32 v40, v32, v33, v34
	v_mov_b32_e32 v35, v46
	v_mov_b32_e32 v32, v47
	v_max3_f32 v40, v40, v35, v32
	s_branch .Lattn_join

.LBB0_454:
	s_bfe_u32 s52, s50, 0x60003
	s_lshl_b32 s44, s52, 21
	s_or_b32 s53, s1, s44
	s_and_b32 s44, s49, 7
	s_lshl_b32 s56, s44, 18
	s_and_b32 s44, s50, 0x1f8
	s_or_b32 s44, s44, s33
	s_and_b32 s51, s50, 7
	s_lshl_b32 s44, s44, 18
	s_add_u32 s44, s2, s44
	v_mov_b32_e32 v48, v133
	s_addc_u32 s45, s3, 0
	s_lshl_b32 s54, s51, 18
	s_add_u32 s54, s31, s54
	v_add_u32_e32 v8, 0x100, v48
	v_add_u32_e32 v16, 0x200, v48
	v_add_u32_e32 v28, 0x300, v48
	v_lshlrev_b32_e32 v0, 4, v48
	v_ashrrev_i32_e32 v32, 3, v48
	v_ashrrev_i32_e32 v36, 3, v8
	v_ashrrev_i32_e32 v40, 3, v16
	v_ashrrev_i32_e32 v44, 3, v28
	s_addc_u32 s55, s38, 0
	v_and_b32_e32 v128, 0x70, v0
	v_ashrrev_i32_e32 v33, 31, v32
	v_ashrrev_i32_e32 v37, 31, v36
	v_ashrrev_i32_e32 v41, 31, v40
	v_ashrrev_i32_e32 v45, 31, v44
	v_lshl_add_u64 v[24:25], s[44:45], 0, v[128:129]
	v_lshl_add_u64 v[26:27], s[54:55], 0, v[128:129]
	v_lshlrev_b64 v[34:35], 11, v[32:33]
	v_lshlrev_b64 v[38:39], 11, v[36:37]
	v_lshlrev_b64 v[42:43], 11, v[40:41]
	v_lshlrev_b64 v[46:47], 11, v[44:45]
	v_lshl_add_u64 v[0:1], v[24:25], 0, v[34:35]
	v_lshl_add_u64 v[4:5], v[26:27], 0, v[34:35]
	v_lshl_add_u64 v[8:9], v[24:25], 0, v[38:39]
	v_lshl_add_u64 v[12:13], v[26:27], 0, v[38:39]
	v_lshl_add_u64 v[16:17], v[24:25], 0, v[42:43]
	v_lshl_add_u64 v[20:21], v[26:27], 0, v[42:43]
	v_lshl_add_u64 v[24:25], v[24:25], 0, v[46:47]
	v_lshl_add_u64 v[28:29], v[26:27], 0, v[46:47]
	global_load_dwordx4 v[0:3], v[0:1], off
	s_nop 0
	global_load_dwordx4 v[4:7], v[4:5], off
	s_nop 0
	global_load_dwordx4 v[8:11], v[8:9], off
	s_nop 0
	global_load_dwordx4 v[12:15], v[12:13], off
	s_nop 0
	global_load_dwordx4 v[16:19], v[16:17], off
	s_nop 0
	global_load_dwordx4 v[20:23], v[20:21], off
	s_nop 0
	global_load_dwordx4 v[24:27], v[24:25], off
	s_nop 0
	global_load_dwordx4 v[28:31], v[28:29], off
	s_add_u32 s44, s39, s53
	v_and_b32_e32 v33, 31, v48
	v_lshrrev_b32_e32 v37, 1, v48
	v_mul_lo_u32 v84, v32, s85
	v_or_b32_e32 v34, v34, v128
	s_addc_u32 s45, s46, 0
	v_or_b32_e32 v38, v38, v128
	v_or_b32_e32 v42, v42, v128
	v_or_b32_e32 v46, v46, v128
	v_or_b32_e32 v32, v33, v81
	v_and_b32_e32 v83, 16, v37
	v_or_b32_e32 v33, v33, v80
	v_add_u32_e32 v37, v128, v84
	v_mul_lo_u32 v87, v36, s85
	s_waitcnt vmcnt(16)
	v_mul_lo_u32 v88, v40, s85
	s_waitcnt vmcnt(9)
	v_mul_lo_u32 v89, v44, s85
	v_lshl_add_u64 v[64:65], s[44:45], 0, v[34:35]
	v_lshl_add_u64 v[66:67], s[44:45], 0, v[38:39]
	v_lshl_add_u64 v[68:69], s[44:45], 0, v[42:43]
	v_lshl_add_u64 v[70:71], s[44:45], 0, v[46:47]
	s_add_u32 s44, s47, s56
	v_mul_lo_u32 v85, v32, s85
	v_mul_u32_u24_e32 v86, 0x90, v33
	v_add_u32_e32 v32, v128, v87
	v_add_u32_e32 v33, v128, v88
	v_add_u32_e32 v36, v128, v89
	s_addc_u32 s45, s48, 0
	v_lshl_add_u64 v[72:73], s[44:45], 0, v[34:35]
	v_lshl_add_u64 v[74:75], s[44:45], 0, v[38:39]
	v_lshl_add_u64 v[76:77], s[44:45], 0, v[42:43]
	v_lshl_add_u64 v[78:79], s[44:45], 0, v[46:47]
	s_mov_b32 s53, 0
	s_mov_b64 s[44:45], 0
	global_load_dwordx4 v[192:195], v[64:65], off
	global_load_dwordx4 v[196:199], v[72:73], off
	global_load_dwordx4 v[200:203], v[66:67], off
	global_load_dwordx4 v[204:207], v[74:75], off
	global_load_dwordx4 v[208:211], v[68:69], off
	global_load_dwordx4 v[212:215], v[76:77], off
	global_load_dwordx4 v[216:219], v[70:71], off
	global_load_dwordx4 v[220:223], v[78:79], off
	s_waitcnt vmcnt(15)
	ds_write_b128 v37, v[0:3]
	s_waitcnt vmcnt(14)
	ds_write_b128 v37, v[4:7] offset:36864
	s_waitcnt vmcnt(13)
	ds_write_b128 v32, v[8:11]
	s_waitcnt vmcnt(12)
	ds_write_b128 v32, v[12:15] offset:36864
	s_waitcnt vmcnt(11)
	ds_write_b128 v33, v[16:19]
	s_waitcnt vmcnt(10)
	ds_write_b128 v33, v[20:23] offset:36864
	s_waitcnt vmcnt(9)
	ds_write_b128 v36, v[24:27]
	s_waitcnt vmcnt(8)
	ds_write_b128 v36, v[28:31] offset:36864
	v_mov_b32_e32 v0, 0
	v_mov_b32_e32 v1, v0
	v_mov_b32_e32 v2, v0
	v_mov_b32_e32 v3, v0
	v_mov_b32_e32 v4, v0
	v_mov_b32_e32 v5, v0
	v_mov_b32_e32 v6, v0
	v_mov_b32_e32 v7, v0
	v_mov_b32_e32 v8, v0
	v_mov_b32_e32 v9, v0
	v_mov_b32_e32 v10, v0
	v_mov_b32_e32 v11, v0
	v_mov_b32_e32 v12, v0
	v_mov_b32_e32 v13, v0
	v_mov_b32_e32 v14, v0
	v_mov_b32_e32 v15, v0
	v_mov_b32_e32 v32, v0
	v_mov_b32_e32 v33, v0
	v_mov_b32_e32 v34, v0
	v_mov_b32_e32 v35, v0
	v_mov_b32_e32 v36, v0
	v_mov_b32_e32 v37, v0
	v_mov_b32_e32 v38, v0
	v_mov_b32_e32 v39, v0
	v_mov_b32_e32 v40, v0
	v_mov_b32_e32 v41, v0
	v_mov_b32_e32 v42, v0
	v_mov_b32_e32 v43, v0
	v_mov_b32_e32 v44, v0
	v_mov_b32_e32 v45, v0
	v_mov_b32_e32 v46, v0
	v_mov_b32_e32 v47, v0
	v_mov_b32_e32 v16, v0
	v_mov_b32_e32 v17, v0
	v_mov_b32_e32 v18, v0
	v_mov_b32_e32 v19, v0
	v_mov_b32_e32 v20, v0
	v_mov_b32_e32 v21, v0
	v_mov_b32_e32 v22, v0
	v_mov_b32_e32 v23, v0
	v_mov_b32_e32 v24, v0
	v_mov_b32_e32 v25, v0
	v_mov_b32_e32 v26, v0
	v_mov_b32_e32 v27, v0
	v_mov_b32_e32 v28, v0
	v_mov_b32_e32 v29, v0
	v_mov_b32_e32 v30, v0
	v_mov_b32_e32 v31, v0
	v_mov_b32_e32 v48, v0
	v_mov_b32_e32 v49, v0
	v_mov_b32_e32 v50, v0
	v_mov_b32_e32 v51, v0
	v_mov_b32_e32 v52, v0
	v_mov_b32_e32 v53, v0
	v_mov_b32_e32 v54, v0
	v_mov_b32_e32 v55, v0
	v_mov_b32_e32 v56, v0
	v_mov_b32_e32 v57, v0
	v_mov_b32_e32 v58, v0
	v_mov_b32_e32 v59, v0
	v_mov_b32_e32 v60, v0
	v_mov_b32_e32 v61, v0
	v_mov_b32_e32 v62, v0
	v_mov_b32_e32 v63, v0
	s_waitcnt lgkmcnt(0)
	s_barrier
	v_add_u32_e32 v240, v85, v83
	v_add_u32_e32 v241, v86, v83
	v_add_u32_e32 v242, v128, v84
	v_add_u32_e32 v243, v128, v87
	v_add_u32_e32 v244, v128, v88
	v_add_u32_e32 v245, v128, v89
.Lmm_win_loop:
	ds_read_b128 v[90:93], v240
	ds_read_b128 v[94:97], v241 offset:36864
	ds_read_b128 v[98:101], v241 offset:41472
	ds_read_b128 v[102:105], v240 offset:4608
	v_lshl_add_u64 v[224:225], v[64:65], 0, s[44:45]
	v_lshl_add_u64 v[226:227], v[72:73], 0, s[44:45]
	v_lshl_add_u64 v[228:229], v[66:67], 0, s[44:45]
	v_lshl_add_u64 v[230:231], v[74:75], 0, s[44:45]
	v_lshl_add_u64 v[232:233], v[68:69], 0, s[44:45]
	v_lshl_add_u64 v[234:235], v[76:77], 0, s[44:45]
	v_lshl_add_u64 v[236:237], v[70:71], 0, s[44:45]
	v_lshl_add_u64 v[238:239], v[78:79], 0, s[44:45]
	global_load_dwordx4 v[142:145], v[224:225], off offset:128
	global_load_dwordx4 v[146:149], v[226:227], off offset:128
	global_load_dwordx4 v[150:153], v[228:229], off offset:128
	global_load_dwordx4 v[154:157], v[230:231], off offset:128
	global_load_dwordx4 v[158:161], v[232:233], off offset:128
	global_load_dwordx4 v[162:165], v[234:235], off offset:128
	global_load_dwordx4 v[166:169], v[236:237], off offset:128
	global_load_dwordx4 v[170:173], v[238:239], off offset:128
	ds_read_b128 v[106:109], v240 offset:32
	ds_read_b128 v[110:113], v241 offset:36896
	ds_read_b128 v[114:117], v241 offset:41504
	ds_read_b128 v[118:121], v240 offset:4640
	s_waitcnt lgkmcnt(4)
	v_mfma_f32_32x32x16_bf16 v[0:15], v[90:93], v[94:97], v[0:15]
	v_mfma_f32_32x32x16_bf16 v[32:47], v[90:93], v[98:101], v[32:47]
	v_mfma_f32_32x32x16_bf16 v[16:31], v[102:105], v[94:97], v[16:31]
	v_mfma_f32_32x32x16_bf16 v[48:63], v[102:105], v[98:101], v[48:63]
	ds_read_b128 v[90:93], v240 offset:64
	ds_read_b128 v[94:97], v241 offset:36928
	ds_read_b128 v[98:101], v241 offset:41536
	ds_read_b128 v[102:105], v240 offset:4672
	s_waitcnt lgkmcnt(4)
	v_mfma_f32_32x32x16_bf16 v[0:15], v[106:109], v[110:113], v[0:15]
	v_mfma_f32_32x32x16_bf16 v[32:47], v[106:109], v[114:117], v[32:47]
	v_mfma_f32_32x32x16_bf16 v[16:31], v[118:121], v[110:113], v[16:31]
	v_mfma_f32_32x32x16_bf16 v[48:63], v[118:121], v[114:117], v[48:63]
	ds_read_b128 v[106:109], v240 offset:96
	ds_read_b128 v[110:113], v241 offset:36960
	ds_read_b128 v[114:117], v241 offset:41568
	ds_read_b128 v[118:121], v240 offset:4704
	s_waitcnt lgkmcnt(4)
	v_mfma_f32_32x32x16_bf16 v[0:15], v[90:93], v[94:97], v[0:15]
	v_mfma_f32_32x32x16_bf16 v[32:47], v[90:93], v[98:101], v[32:47]
	v_mfma_f32_32x32x16_bf16 v[16:31], v[102:105], v[94:97], v[16:31]
	v_mfma_f32_32x32x16_bf16 v[48:63], v[102:105], v[98:101], v[48:63]
	s_add_u32 s44, s44, 0x80
	s_addc_u32 s45, s45, 0
	s_waitcnt vmcnt(8)
	ds_write_b128 v242, v[192:195] offset:18432
	ds_write_b128 v242, v[196:199] offset:55296
	ds_write_b128 v243, v[200:203] offset:18432
	ds_write_b128 v243, v[204:207] offset:55296
	s_waitcnt lgkmcnt(4)
	v_mfma_f32_32x32x16_bf16 v[0:15], v[106:109], v[110:113], v[0:15]
	v_mfma_f32_32x32x16_bf16 v[32:47], v[106:109], v[114:117], v[32:47]
	ds_write_b128 v244, v[208:211] offset:18432
	ds_write_b128 v244, v[212:215] offset:55296
	ds_write_b128 v245, v[216:219] offset:18432
	ds_write_b128 v245, v[220:223] offset:55296
	v_mfma_f32_32x32x16_bf16 v[16:31], v[118:121], v[110:113], v[16:31]
	v_mfma_f32_32x32x16_bf16 v[48:63], v[118:121], v[114:117], v[48:63]
	s_waitcnt lgkmcnt(0)
	s_barrier
	ds_read_b128 v[90:93], v240 offset:18432
	ds_read_b128 v[94:97], v241 offset:55296
	ds_read_b128 v[98:101], v241 offset:59904
	ds_read_b128 v[102:105], v240 offset:23040
	v_lshl_add_u64 v[224:225], v[64:65], 0, s[44:45]
	v_lshl_add_u64 v[226:227], v[72:73], 0, s[44:45]
	v_lshl_add_u64 v[228:229], v[66:67], 0, s[44:45]
	v_lshl_add_u64 v[230:231], v[74:75], 0, s[44:45]
	v_lshl_add_u64 v[232:233], v[68:69], 0, s[44:45]
	v_lshl_add_u64 v[234:235], v[76:77], 0, s[44:45]
	v_lshl_add_u64 v[236:237], v[70:71], 0, s[44:45]
	v_lshl_add_u64 v[238:239], v[78:79], 0, s[44:45]
	global_load_dwordx4 v[192:195], v[224:225], off offset:128
	global_load_dwordx4 v[196:199], v[226:227], off offset:128
	global_load_dwordx4 v[200:203], v[228:229], off offset:128
	global_load_dwordx4 v[204:207], v[230:231], off offset:128
	global_load_dwordx4 v[208:211], v[232:233], off offset:128
	global_load_dwordx4 v[212:215], v[234:235], off offset:128
	global_load_dwordx4 v[216:219], v[236:237], off offset:128
	global_load_dwordx4 v[220:223], v[238:239], off offset:128
	ds_read_b128 v[106:109], v240 offset:18464
	ds_read_b128 v[110:113], v241 offset:55328
	ds_read_b128 v[114:117], v241 offset:59936
	ds_read_b128 v[118:121], v240 offset:23072
	s_waitcnt lgkmcnt(4)
	v_mfma_f32_32x32x16_bf16 v[0:15], v[90:93], v[94:97], v[0:15]
	v_mfma_f32_32x32x16_bf16 v[32:47], v[90:93], v[98:101], v[32:47]
	v_mfma_f32_32x32x16_bf16 v[16:31], v[102:105], v[94:97], v[16:31]
	v_mfma_f32_32x32x16_bf16 v[48:63], v[102:105], v[98:101], v[48:63]
	ds_read_b128 v[90:93], v240 offset:18496
	ds_read_b128 v[94:97], v241 offset:55360
	ds_read_b128 v[98:101], v241 offset:59968
	ds_read_b128 v[102:105], v240 offset:23104
	s_waitcnt lgkmcnt(4)
	v_mfma_f32_32x32x16_bf16 v[0:15], v[106:109], v[110:113], v[0:15]
	v_mfma_f32_32x32x16_bf16 v[32:47], v[106:109], v[114:117], v[32:47]
	v_mfma_f32_32x32x16_bf16 v[16:31], v[118:121], v[110:113], v[16:31]
	v_mfma_f32_32x32x16_bf16 v[48:63], v[118:121], v[114:117], v[48:63]
	ds_read_b128 v[106:109], v240 offset:18528
	ds_read_b128 v[110:113], v241 offset:55392
	ds_read_b128 v[114:117], v241 offset:60000
	ds_read_b128 v[118:121], v240 offset:23136
	s_waitcnt lgkmcnt(4)
	v_mfma_f32_32x32x16_bf16 v[0:15], v[90:93], v[94:97], v[0:15]
	v_mfma_f32_32x32x16_bf16 v[32:47], v[90:93], v[98:101], v[32:47]
	v_mfma_f32_32x32x16_bf16 v[16:31], v[102:105], v[94:97], v[16:31]
	v_mfma_f32_32x32x16_bf16 v[48:63], v[102:105], v[98:101], v[48:63]
	s_add_u32 s44, s44, 0x80
	s_addc_u32 s45, s45, 0
	s_waitcnt vmcnt(8)
	ds_write_b128 v242, v[142:145]
	ds_write_b128 v242, v[146:149] offset:36864
	ds_write_b128 v243, v[150:153]
	ds_write_b128 v243, v[154:157] offset:36864
	s_waitcnt lgkmcnt(4)
	v_mfma_f32_32x32x16_bf16 v[0:15], v[106:109], v[110:113], v[0:15]
	v_mfma_f32_32x32x16_bf16 v[32:47], v[106:109], v[114:117], v[32:47]
	ds_write_b128 v244, v[158:161]
	ds_write_b128 v244, v[162:165] offset:36864
	ds_write_b128 v245, v[166:169]
	ds_write_b128 v245, v[170:173] offset:36864
	v_mfma_f32_32x32x16_bf16 v[16:31], v[118:121], v[110:113], v[16:31]
	v_mfma_f32_32x32x16_bf16 v[48:63], v[118:121], v[114:117], v[48:63]
	s_waitcnt lgkmcnt(0)
	s_barrier
	s_cmpk_lg_i32 s44, 0x700
	s_cbranch_scc1 .Lmm_win_loop
	ds_read_b128 v[90:93], v240
	ds_read_b128 v[94:97], v241 offset:36864
	ds_read_b128 v[98:101], v241 offset:41472
	ds_read_b128 v[102:105], v240 offset:4608
	ds_read_b128 v[106:109], v240 offset:32
	ds_read_b128 v[110:113], v241 offset:36896
	ds_read_b128 v[114:117], v241 offset:41504
	ds_read_b128 v[118:121], v240 offset:4640
	s_waitcnt lgkmcnt(4)
	v_mfma_f32_32x32x16_bf16 v[0:15], v[90:93], v[94:97], v[0:15]
	v_mfma_f32_32x32x16_bf16 v[32:47], v[90:93], v[98:101], v[32:47]
	v_mfma_f32_32x32x16_bf16 v[16:31], v[102:105], v[94:97], v[16:31]
	v_mfma_f32_32x32x16_bf16 v[48:63], v[102:105], v[98:101], v[48:63]
	ds_read_b128 v[90:93], v240 offset:64
	ds_read_b128 v[94:97], v241 offset:36928
	ds_read_b128 v[98:101], v241 offset:41536
	ds_read_b128 v[102:105], v240 offset:4672
	s_waitcnt lgkmcnt(4)
	v_mfma_f32_32x32x16_bf16 v[0:15], v[106:109], v[110:113], v[0:15]
	v_mfma_f32_32x32x16_bf16 v[32:47], v[106:109], v[114:117], v[32:47]
	v_mfma_f32_32x32x16_bf16 v[16:31], v[118:121], v[110:113], v[16:31]
	v_mfma_f32_32x32x16_bf16 v[48:63], v[118:121], v[114:117], v[48:63]
	ds_read_b128 v[106:109], v240 offset:96
	ds_read_b128 v[110:113], v241 offset:36960
	ds_read_b128 v[114:117], v241 offset:41568
	ds_read_b128 v[118:121], v240 offset:4704
	s_waitcnt lgkmcnt(4)
	v_mfma_f32_32x32x16_bf16 v[0:15], v[90:93], v[94:97], v[0:15]
	v_mfma_f32_32x32x16_bf16 v[32:47], v[90:93], v[98:101], v[32:47]
	v_mfma_f32_32x32x16_bf16 v[16:31], v[102:105], v[94:97], v[16:31]
	v_mfma_f32_32x32x16_bf16 v[48:63], v[102:105], v[98:101], v[48:63]
	s_waitcnt vmcnt(0)
	ds_write_b128 v242, v[192:195] offset:18432
	ds_write_b128 v242, v[196:199] offset:55296
	ds_write_b128 v243, v[200:203] offset:18432
	ds_write_b128 v243, v[204:207] offset:55296
	s_waitcnt lgkmcnt(4)
	v_mfma_f32_32x32x16_bf16 v[0:15], v[106:109], v[110:113], v[0:15]
	v_mfma_f32_32x32x16_bf16 v[32:47], v[106:109], v[114:117], v[32:47]
	ds_write_b128 v244, v[208:211] offset:18432
	ds_write_b128 v244, v[212:215] offset:55296
	ds_write_b128 v245, v[216:219] offset:18432
	ds_write_b128 v245, v[220:223] offset:55296
	v_mfma_f32_32x32x16_bf16 v[16:31], v[118:121], v[110:113], v[16:31]
	v_mfma_f32_32x32x16_bf16 v[48:63], v[118:121], v[114:117], v[48:63]
	s_waitcnt lgkmcnt(0)
	s_barrier
	ds_read_b128 v[90:93], v240 offset:18432
	ds_read_b128 v[94:97], v241 offset:55296
	ds_read_b128 v[98:101], v241 offset:59904
	ds_read_b128 v[102:105], v240 offset:23040
	ds_read_b128 v[106:109], v240 offset:18464
	ds_read_b128 v[110:113], v241 offset:55328
	ds_read_b128 v[114:117], v241 offset:59936
	ds_read_b128 v[118:121], v240 offset:23072
	s_waitcnt lgkmcnt(4)
	v_mfma_f32_32x32x16_bf16 v[0:15], v[90:93], v[94:97], v[0:15]
	v_mfma_f32_32x32x16_bf16 v[32:47], v[90:93], v[98:101], v[32:47]
	v_mfma_f32_32x32x16_bf16 v[16:31], v[102:105], v[94:97], v[16:31]
	v_mfma_f32_32x32x16_bf16 v[48:63], v[102:105], v[98:101], v[48:63]
	ds_read_b128 v[90:93], v240 offset:18496
	ds_read_b128 v[94:97], v241 offset:55360
	ds_read_b128 v[98:101], v241 offset:59968
	ds_read_b128 v[102:105], v240 offset:23104
	s_waitcnt lgkmcnt(4)
	v_mfma_f32_32x32x16_bf16 v[0:15], v[106:109], v[110:113], v[0:15]
	v_mfma_f32_32x32x16_bf16 v[32:47], v[106:109], v[114:117], v[32:47]
	v_mfma_f32_32x32x16_bf16 v[16:31], v[118:121], v[110:113], v[16:31]
	v_mfma_f32_32x32x16_bf16 v[48:63], v[118:121], v[114:117], v[48:63]
	ds_read_b128 v[106:109], v240 offset:18528
	ds_read_b128 v[110:113], v241 offset:55392
	ds_read_b128 v[114:117], v241 offset:60000
	ds_read_b128 v[118:121], v240 offset:23136
	s_waitcnt lgkmcnt(4)
	v_mfma_f32_32x32x16_bf16 v[0:15], v[90:93], v[94:97], v[0:15]
	v_mfma_f32_32x32x16_bf16 v[32:47], v[90:93], v[98:101], v[32:47]
	v_mfma_f32_32x32x16_bf16 v[16:31], v[102:105], v[94:97], v[16:31]
	v_mfma_f32_32x32x16_bf16 v[48:63], v[102:105], v[98:101], v[48:63]
	s_waitcnt lgkmcnt(0)
	s_barrier
	v_mfma_f32_32x32x16_bf16 v[0:15], v[106:109], v[110:113], v[0:15]
	v_mfma_f32_32x32x16_bf16 v[32:47], v[106:109], v[114:117], v[32:47]
	v_mfma_f32_32x32x16_bf16 v[16:31], v[118:121], v[110:113], v[16:31]
	v_mfma_f32_32x32x16_bf16 v[48:63], v[118:121], v[114:117], v[48:63]
	s_nop 15
	s_lshl_b32 s44, s52, 10
	v_mov_b32_e32 v64, v133
	v_mov_b32_e32 v65, v133
	s_nop 0
	v_lshrrev_b32_e32 v65, 6, v65
	v_and_b32_e32 v66, 31, v64
	v_mul_lo_u32 v65, v65, s6
	v_lshrrev_b32_e32 v67, 3, v64
	v_and_b32_e32 v67, 4, v67
	v_lshl_or_b32 v66, v66, 2, v65
	v_mad_u32_u24 v66, v67, s7, v66
	s_nop 0
	ds_write2_b32 v66, v0, v32 offset1:32
	ds_write2_b32 v66, v1, v33 offset0:68 offset1:100
	ds_write2_b32 v66, v2, v34 offset0:136 offset1:168
	ds_write2_b32 v66, v3, v35 offset0:204 offset1:236
	v_add_u32_e32 v0, 0x800, v66
	ds_write2_b32 v0, v4, v36 offset0:32 offset1:64
	ds_write2_b32 v0, v5, v37 offset0:100 offset1:132
	ds_write2_b32 v0, v6, v38 offset0:168 offset1:200
	v_add_u32_e32 v0, 0xa00, v66
	ds_write2_b32 v0, v7, v39 offset0:108 offset1:140
	v_add_u32_e32 v0, 0x1000, v66
	ds_write2_b32 v0, v8, v40 offset0:64 offset1:96
	ds_write2_b32 v0, v9, v41 offset0:132 offset1:164
	ds_write2_b32 v0, v10, v42 offset0:200 offset1:232
	v_add_u32_e32 v0, 0x1400, v66
	ds_write2_b32 v0, v11, v43 offset0:12 offset1:44
	v_add_u32_e32 v0, 0x1800, v66
	ds_write2_b32 v0, v12, v44 offset0:96 offset1:128
	ds_write2_b32 v0, v13, v45 offset0:164 offset1:196
	v_add_u32_e32 v0, 0x1a00, v66
	ds_write2_b32 v0, v14, v46 offset0:104 offset1:136
	v_add_u32_e32 v0, 0x1c00, v66
	ds_write2_b32 v0, v15, v47 offset0:44 offset1:76
	v_add_u32_e32 v0, 0x2000, v66
	s_nop 1
	ds_write2_b32 v0, v16, v48 offset0:128 offset1:160
	ds_write2_b32 v0, v17, v49 offset0:196 offset1:228
	v_add_u32_e32 v0, 0x2400, v66
	ds_write2_b32 v0, v18, v50 offset0:8 offset1:40
	ds_write2_b32 v0, v19, v51 offset0:76 offset1:108
	v_add_u32_e32 v0, 0x2800, v66
	ds_write2_b32 v0, v20, v52 offset0:160 offset1:192
	v_add_u32_e32 v0, 0x2a00, v66
	ds_write2_b32 v0, v21, v53 offset0:100 offset1:132
	v_add_u32_e32 v0, 0x2c00, v66
	ds_write2_b32 v0, v22, v54 offset0:40 offset1:72
	ds_write2_b32 v0, v23, v55 offset0:108 offset1:140
	v_add_u32_e32 v0, 0x3000, v66
	ds_write2_b32 v0, v24, v56 offset0:192 offset1:224
	v_add_u32_e32 v0, 0x3400, v66
	ds_write2_b32 v0, v25, v57 offset0:4 offset1:36
	ds_write2_b32 v0, v26, v58 offset0:72 offset1:104
	ds_write2_b32 v0, v27, v59 offset0:140 offset1:172
	v_add_u32_e32 v0, 0x3a00, v66
	ds_write2_b32 v0, v28, v60 offset0:96 offset1:128
	v_add_u32_e32 v0, 0x3c00, v66
	ds_write2_b32 v0, v29, v61 offset0:36 offset1:68
	ds_write2_b32 v0, v30, v62 offset0:104 offset1:136
	ds_write2_b32 v0, v31, v63 offset0:172 offset1:204
	v_lshlrev_b32_e32 v0, 1, v80
	v_bfe_u32 v3, v64, 3, 3
	v_lshl_or_b32 v128, s51, 8, v0
	v_lshlrev_b32_e32 v2, 4, v64
	v_and_b32_e32 v4, 7, v64
	v_lshl_add_u64 v[0:1], s[42:43], 0, v[128:129]
	v_and_b32_e32 v128, 0x70, v2
	v_add3_u32 v2, v82, s44, v3
	v_mul_u32_u24_e32 v3, 0x110, v3
	v_lshlrev_b32_e32 v4, 5, v4
	v_lshl_add_u64 v[0:1], v[0:1], 0, v[128:129]
	v_add3_u32 v4, v65, v3, v4
	s_mov_b32 s44, 0

.LBB0_783:
	s_bfe_u32 s47, s53, 0x60004
	s_lshl_b32 s42, s47, 21
	s_or_b32 s56, s1, s42
	s_and_b32 s42, s52, 15
	s_lshl_b32 s57, s42, 18
	s_lshr_b32 s42, s53, 1
	s_and_b32 s42, s42, 0x1f8
	s_or_b32 s42, s42, s33
	s_and_b32 s46, s53, 15
	s_lshl_b32 s42, s42, 18
	s_add_u32 s42, s3, s42
	v_mov_b32_e32 v48, v133
	s_addc_u32 s43, s31, 0
	s_lshl_b32 s54, s46, 18
	s_add_u32 s54, s38, s54
	v_add_u32_e32 v8, 0x100, v48
	v_add_u32_e32 v16, 0x200, v48
	v_add_u32_e32 v28, 0x300, v48
	v_lshlrev_b32_e32 v0, 4, v48
	v_ashrrev_i32_e32 v32, 3, v48
	v_ashrrev_i32_e32 v36, 3, v8
	v_ashrrev_i32_e32 v40, 3, v16
	v_ashrrev_i32_e32 v44, 3, v28
	s_addc_u32 s55, s39, 0
	v_and_b32_e32 v128, 0x70, v0
	v_ashrrev_i32_e32 v33, 31, v32
	v_ashrrev_i32_e32 v37, 31, v36
	v_ashrrev_i32_e32 v41, 31, v40
	v_ashrrev_i32_e32 v45, 31, v44
	v_lshl_add_u64 v[24:25], s[42:43], 0, v[128:129]
	v_lshl_add_u64 v[26:27], s[54:55], 0, v[128:129]
	v_lshlrev_b64 v[34:35], 11, v[32:33]
	v_lshlrev_b64 v[38:39], 11, v[36:37]
	v_lshlrev_b64 v[42:43], 11, v[40:41]
	v_lshlrev_b64 v[46:47], 11, v[44:45]
	v_lshl_add_u64 v[0:1], v[24:25], 0, v[34:35]
	v_lshl_add_u64 v[4:5], v[26:27], 0, v[34:35]
	v_lshl_add_u64 v[8:9], v[24:25], 0, v[38:39]
	v_lshl_add_u64 v[12:13], v[26:27], 0, v[38:39]
	v_lshl_add_u64 v[16:17], v[24:25], 0, v[42:43]
	v_lshl_add_u64 v[20:21], v[26:27], 0, v[42:43]
	v_lshl_add_u64 v[24:25], v[24:25], 0, v[46:47]
	v_lshl_add_u64 v[28:29], v[26:27], 0, v[46:47]
	global_load_dwordx4 v[0:3], v[0:1], off
	s_nop 0
	global_load_dwordx4 v[4:7], v[4:5], off
	s_nop 0
	global_load_dwordx4 v[8:11], v[8:9], off
	s_nop 0
	global_load_dwordx4 v[12:15], v[12:13], off
	s_nop 0
	global_load_dwordx4 v[16:19], v[16:17], off
	s_nop 0
	global_load_dwordx4 v[20:23], v[20:21], off
	s_nop 0
	global_load_dwordx4 v[24:27], v[24:25], off
	s_nop 0
	global_load_dwordx4 v[28:31], v[28:29], off
	s_add_u32 s42, s48, s56
	v_and_b32_e32 v33, 31, v48
	v_lshrrev_b32_e32 v37, 1, v48
	v_mul_lo_u32 v84, v32, s85
	v_or_b32_e32 v34, v34, v128
	s_addc_u32 s43, s49, 0
	v_or_b32_e32 v38, v38, v128
	v_or_b32_e32 v42, v42, v128
	v_or_b32_e32 v46, v46, v128
	v_or_b32_e32 v32, v33, v81
	v_and_b32_e32 v83, 16, v37
	v_or_b32_e32 v33, v33, v80
	v_add_u32_e32 v37, v128, v84
	v_mul_lo_u32 v87, v36, s85
	s_waitcnt vmcnt(16)
	v_mul_lo_u32 v88, v40, s85
	s_waitcnt vmcnt(9)
	v_mul_lo_u32 v89, v44, s85
	v_lshl_add_u64 v[64:65], s[42:43], 0, v[34:35]
	v_lshl_add_u64 v[66:67], s[42:43], 0, v[38:39]
	v_lshl_add_u64 v[68:69], s[42:43], 0, v[42:43]
	v_lshl_add_u64 v[70:71], s[42:43], 0, v[46:47]
	s_add_u32 s42, s50, s57
	v_mul_lo_u32 v85, v32, s85
	v_mul_u32_u24_e32 v86, 0x90, v33
	v_add_u32_e32 v32, v128, v87
	v_add_u32_e32 v33, v128, v88
	v_add_u32_e32 v36, v128, v89
	s_addc_u32 s43, s51, 0
	v_lshl_add_u64 v[72:73], s[42:43], 0, v[34:35]
	v_lshl_add_u64 v[74:75], s[42:43], 0, v[38:39]
	v_lshl_add_u64 v[76:77], s[42:43], 0, v[42:43]
	v_lshl_add_u64 v[78:79], s[42:43], 0, v[46:47]
	s_mov_b32 s54, 0
	s_mov_b64 s[42:43], 0
	global_load_dwordx4 v[192:195], v[64:65], off
	global_load_dwordx4 v[196:199], v[72:73], off
	global_load_dwordx4 v[200:203], v[66:67], off
	global_load_dwordx4 v[204:207], v[74:75], off
	global_load_dwordx4 v[208:211], v[68:69], off
	global_load_dwordx4 v[212:215], v[76:77], off
	global_load_dwordx4 v[216:219], v[70:71], off
	global_load_dwordx4 v[220:223], v[78:79], off
	s_waitcnt vmcnt(15)
	ds_write_b128 v37, v[0:3]
	s_waitcnt vmcnt(14)
	ds_write_b128 v37, v[4:7] offset:36864
	s_waitcnt vmcnt(13)
	ds_write_b128 v32, v[8:11]
	s_waitcnt vmcnt(12)
	ds_write_b128 v32, v[12:15] offset:36864
	s_waitcnt vmcnt(11)
	ds_write_b128 v33, v[16:19]
	s_waitcnt vmcnt(10)
	ds_write_b128 v33, v[20:23] offset:36864
	s_waitcnt vmcnt(9)
	ds_write_b128 v36, v[24:27]
	s_waitcnt vmcnt(8)
	ds_write_b128 v36, v[28:31] offset:36864
	v_mov_b32_e32 v0, 0
	v_mov_b32_e32 v1, v0
	v_mov_b32_e32 v2, v0
	v_mov_b32_e32 v3, v0
	v_mov_b32_e32 v4, v0
	v_mov_b32_e32 v5, v0
	v_mov_b32_e32 v6, v0
	v_mov_b32_e32 v7, v0
	v_mov_b32_e32 v8, v0
	v_mov_b32_e32 v9, v0
	v_mov_b32_e32 v10, v0
	v_mov_b32_e32 v11, v0
	v_mov_b32_e32 v12, v0
	v_mov_b32_e32 v13, v0
	v_mov_b32_e32 v14, v0
	v_mov_b32_e32 v15, v0
	v_mov_b32_e32 v32, v0
	v_mov_b32_e32 v33, v0
	v_mov_b32_e32 v34, v0
	v_mov_b32_e32 v35, v0
	v_mov_b32_e32 v36, v0
	v_mov_b32_e32 v37, v0
	v_mov_b32_e32 v38, v0
	v_mov_b32_e32 v39, v0
	v_mov_b32_e32 v40, v0
	v_mov_b32_e32 v41, v0
	v_mov_b32_e32 v42, v0
	v_mov_b32_e32 v43, v0
	v_mov_b32_e32 v44, v0
	v_mov_b32_e32 v45, v0
	v_mov_b32_e32 v46, v0
	v_mov_b32_e32 v47, v0
	v_mov_b32_e32 v16, v0
	v_mov_b32_e32 v17, v0
	v_mov_b32_e32 v18, v0
	v_mov_b32_e32 v19, v0
	v_mov_b32_e32 v20, v0
	v_mov_b32_e32 v21, v0
	v_mov_b32_e32 v22, v0
	v_mov_b32_e32 v23, v0
	v_mov_b32_e32 v24, v0
	v_mov_b32_e32 v25, v0
	v_mov_b32_e32 v26, v0
	v_mov_b32_e32 v27, v0
	v_mov_b32_e32 v28, v0
	v_mov_b32_e32 v29, v0
	v_mov_b32_e32 v30, v0
	v_mov_b32_e32 v31, v0
	v_mov_b32_e32 v48, v0
	v_mov_b32_e32 v49, v0
	v_mov_b32_e32 v50, v0
	v_mov_b32_e32 v51, v0
	v_mov_b32_e32 v52, v0
	v_mov_b32_e32 v53, v0
	v_mov_b32_e32 v54, v0
	v_mov_b32_e32 v55, v0
	v_mov_b32_e32 v56, v0
	v_mov_b32_e32 v57, v0
	v_mov_b32_e32 v58, v0
	v_mov_b32_e32 v59, v0
	v_mov_b32_e32 v60, v0
	v_mov_b32_e32 v61, v0
	v_mov_b32_e32 v62, v0
	v_mov_b32_e32 v63, v0
	s_waitcnt lgkmcnt(0)
	s_barrier
	v_add_u32_e32 v240, v85, v83
	v_add_u32_e32 v241, v86, v83
	v_add_u32_e32 v242, v128, v84
	v_add_u32_e32 v243, v128, v87
	v_add_u32_e32 v244, v128, v88
	v_add_u32_e32 v245, v128, v89
.Lmm_glu_loop:
	ds_read_b128 v[90:93], v240
	ds_read_b128 v[94:97], v241 offset:36864
	ds_read_b128 v[98:101], v241 offset:41472
	ds_read_b128 v[102:105], v240 offset:4608
	v_lshl_add_u64 v[224:225], v[64:65], 0, s[42:43]
	v_lshl_add_u64 v[226:227], v[72:73], 0, s[42:43]
	v_lshl_add_u64 v[228:229], v[66:67], 0, s[42:43]
	v_lshl_add_u64 v[230:231], v[74:75], 0, s[42:43]
	v_lshl_add_u64 v[232:233], v[68:69], 0, s[42:43]
	v_lshl_add_u64 v[234:235], v[76:77], 0, s[42:43]
	v_lshl_add_u64 v[236:237], v[70:71], 0, s[42:43]
	v_lshl_add_u64 v[238:239], v[78:79], 0, s[42:43]
	global_load_dwordx4 v[142:145], v[224:225], off offset:128
	global_load_dwordx4 v[146:149], v[226:227], off offset:128
	global_load_dwordx4 v[150:153], v[228:229], off offset:128
	global_load_dwordx4 v[154:157], v[230:231], off offset:128
	global_load_dwordx4 v[158:161], v[232:233], off offset:128
	global_load_dwordx4 v[162:165], v[234:235], off offset:128
	global_load_dwordx4 v[166:169], v[236:237], off offset:128
	global_load_dwordx4 v[170:173], v[238:239], off offset:128
	ds_read_b128 v[106:109], v240 offset:32
	ds_read_b128 v[110:113], v241 offset:36896
	ds_read_b128 v[114:117], v241 offset:41504
	ds_read_b128 v[118:121], v240 offset:4640
	s_waitcnt lgkmcnt(4)
	v_mfma_f32_32x32x16_bf16 v[0:15], v[90:93], v[94:97], v[0:15]
	v_mfma_f32_32x32x16_bf16 v[32:47], v[90:93], v[98:101], v[32:47]
	v_mfma_f32_32x32x16_bf16 v[16:31], v[102:105], v[94:97], v[16:31]
	v_mfma_f32_32x32x16_bf16 v[48:63], v[102:105], v[98:101], v[48:63]
	ds_read_b128 v[90:93], v240 offset:64
	ds_read_b128 v[94:97], v241 offset:36928
	ds_read_b128 v[98:101], v241 offset:41536
	ds_read_b128 v[102:105], v240 offset:4672
	s_waitcnt lgkmcnt(4)
	v_mfma_f32_32x32x16_bf16 v[0:15], v[106:109], v[110:113], v[0:15]
	v_mfma_f32_32x32x16_bf16 v[32:47], v[106:109], v[114:117], v[32:47]
	v_mfma_f32_32x32x16_bf16 v[16:31], v[118:121], v[110:113], v[16:31]
	v_mfma_f32_32x32x16_bf16 v[48:63], v[118:121], v[114:117], v[48:63]
	ds_read_b128 v[106:109], v240 offset:96
	ds_read_b128 v[110:113], v241 offset:36960
	ds_read_b128 v[114:117], v241 offset:41568
	ds_read_b128 v[118:121], v240 offset:4704
	s_waitcnt lgkmcnt(4)
	v_mfma_f32_32x32x16_bf16 v[0:15], v[90:93], v[94:97], v[0:15]
	v_mfma_f32_32x32x16_bf16 v[32:47], v[90:93], v[98:101], v[32:47]
	v_mfma_f32_32x32x16_bf16 v[16:31], v[102:105], v[94:97], v[16:31]
	v_mfma_f32_32x32x16_bf16 v[48:63], v[102:105], v[98:101], v[48:63]
	s_add_u32 s42, s42, 0x80
	s_addc_u32 s43, s43, 0
	s_waitcnt vmcnt(8)
	ds_write_b128 v242, v[192:195] offset:18432
	ds_write_b128 v242, v[196:199] offset:55296
	ds_write_b128 v243, v[200:203] offset:18432
	ds_write_b128 v243, v[204:207] offset:55296
	s_waitcnt lgkmcnt(4)
	v_mfma_f32_32x32x16_bf16 v[0:15], v[106:109], v[110:113], v[0:15]
	v_mfma_f32_32x32x16_bf16 v[32:47], v[106:109], v[114:117], v[32:47]
	ds_write_b128 v244, v[208:211] offset:18432
	ds_write_b128 v244, v[212:215] offset:55296
	ds_write_b128 v245, v[216:219] offset:18432
	ds_write_b128 v245, v[220:223] offset:55296
	v_mfma_f32_32x32x16_bf16 v[16:31], v[118:121], v[110:113], v[16:31]
	v_mfma_f32_32x32x16_bf16 v[48:63], v[118:121], v[114:117], v[48:63]
	s_waitcnt lgkmcnt(0)
	s_barrier
	ds_read_b128 v[90:93], v240 offset:18432
	ds_read_b128 v[94:97], v241 offset:55296
	ds_read_b128 v[98:101], v241 offset:59904
	ds_read_b128 v[102:105], v240 offset:23040
	v_lshl_add_u64 v[224:225], v[64:65], 0, s[42:43]
	v_lshl_add_u64 v[226:227], v[72:73], 0, s[42:43]
	v_lshl_add_u64 v[228:229], v[66:67], 0, s[42:43]
	v_lshl_add_u64 v[230:231], v[74:75], 0, s[42:43]
	v_lshl_add_u64 v[232:233], v[68:69], 0, s[42:43]
	v_lshl_add_u64 v[234:235], v[76:77], 0, s[42:43]
	v_lshl_add_u64 v[236:237], v[70:71], 0, s[42:43]
	v_lshl_add_u64 v[238:239], v[78:79], 0, s[42:43]
	global_load_dwordx4 v[192:195], v[224:225], off offset:128
	global_load_dwordx4 v[196:199], v[226:227], off offset:128
	global_load_dwordx4 v[200:203], v[228:229], off offset:128
	global_load_dwordx4 v[204:207], v[230:231], off offset:128
	global_load_dwordx4 v[208:211], v[232:233], off offset:128
	global_load_dwordx4 v[212:215], v[234:235], off offset:128
	global_load_dwordx4 v[216:219], v[236:237], off offset:128
	global_load_dwordx4 v[220:223], v[238:239], off offset:128
	ds_read_b128 v[106:109], v240 offset:18464
	ds_read_b128 v[110:113], v241 offset:55328
	ds_read_b128 v[114:117], v241 offset:59936
	ds_read_b128 v[118:121], v240 offset:23072
	s_waitcnt lgkmcnt(4)
	v_mfma_f32_32x32x16_bf16 v[0:15], v[90:93], v[94:97], v[0:15]
	v_mfma_f32_32x32x16_bf16 v[32:47], v[90:93], v[98:101], v[32:47]
	v_mfma_f32_32x32x16_bf16 v[16:31], v[102:105], v[94:97], v[16:31]
	v_mfma_f32_32x32x16_bf16 v[48:63], v[102:105], v[98:101], v[48:63]
	ds_read_b128 v[90:93], v240 offset:18496
	ds_read_b128 v[94:97], v241 offset:55360
	ds_read_b128 v[98:101], v241 offset:59968
	ds_read_b128 v[102:105], v240 offset:23104
	s_waitcnt lgkmcnt(4)
	v_mfma_f32_32x32x16_bf16 v[0:15], v[106:109], v[110:113], v[0:15]
	v_mfma_f32_32x32x16_bf16 v[32:47], v[106:109], v[114:117], v[32:47]
	v_mfma_f32_32x32x16_bf16 v[16:31], v[118:121], v[110:113], v[16:31]
	v_mfma_f32_32x32x16_bf16 v[48:63], v[118:121], v[114:117], v[48:63]
	ds_read_b128 v[106:109], v240 offset:18528
	ds_read_b128 v[110:113], v241 offset:55392
	ds_read_b128 v[114:117], v241 offset:60000
	ds_read_b128 v[118:121], v240 offset:23136
	s_waitcnt lgkmcnt(4)
	v_mfma_f32_32x32x16_bf16 v[0:15], v[90:93], v[94:97], v[0:15]
	v_mfma_f32_32x32x16_bf16 v[32:47], v[90:93], v[98:101], v[32:47]
	v_mfma_f32_32x32x16_bf16 v[16:31], v[102:105], v[94:97], v[16:31]
	v_mfma_f32_32x32x16_bf16 v[48:63], v[102:105], v[98:101], v[48:63]
	s_add_u32 s42, s42, 0x80
	s_addc_u32 s43, s43, 0
	s_waitcnt vmcnt(8)
	ds_write_b128 v242, v[142:145]
	ds_write_b128 v242, v[146:149] offset:36864
	ds_write_b128 v243, v[150:153]
	ds_write_b128 v243, v[154:157] offset:36864
	s_waitcnt lgkmcnt(4)
	v_mfma_f32_32x32x16_bf16 v[0:15], v[106:109], v[110:113], v[0:15]
	v_mfma_f32_32x32x16_bf16 v[32:47], v[106:109], v[114:117], v[32:47]
	ds_write_b128 v244, v[158:161]
	ds_write_b128 v244, v[162:165] offset:36864
	ds_write_b128 v245, v[166:169]
	ds_write_b128 v245, v[170:173] offset:36864
	v_mfma_f32_32x32x16_bf16 v[16:31], v[118:121], v[110:113], v[16:31]
	v_mfma_f32_32x32x16_bf16 v[48:63], v[118:121], v[114:117], v[48:63]
	s_waitcnt lgkmcnt(0)
	s_barrier
	s_cmpk_lg_i32 s42, 0x700
	s_cbranch_scc1 .Lmm_glu_loop
	ds_read_b128 v[90:93], v240
	ds_read_b128 v[94:97], v241 offset:36864
	ds_read_b128 v[98:101], v241 offset:41472
	ds_read_b128 v[102:105], v240 offset:4608
	ds_read_b128 v[106:109], v240 offset:32
	ds_read_b128 v[110:113], v241 offset:36896
	ds_read_b128 v[114:117], v241 offset:41504
	ds_read_b128 v[118:121], v240 offset:4640
	s_waitcnt lgkmcnt(4)
	v_mfma_f32_32x32x16_bf16 v[0:15], v[90:93], v[94:97], v[0:15]
	v_mfma_f32_32x32x16_bf16 v[32:47], v[90:93], v[98:101], v[32:47]
	v_mfma_f32_32x32x16_bf16 v[16:31], v[102:105], v[94:97], v[16:31]
	v_mfma_f32_32x32x16_bf16 v[48:63], v[102:105], v[98:101], v[48:63]
	ds_read_b128 v[90:93], v240 offset:64
	ds_read_b128 v[94:97], v241 offset:36928
	ds_read_b128 v[98:101], v241 offset:41536
	ds_read_b128 v[102:105], v240 offset:4672
	s_waitcnt lgkmcnt(4)
	v_mfma_f32_32x32x16_bf16 v[0:15], v[106:109], v[110:113], v[0:15]
	v_mfma_f32_32x32x16_bf16 v[32:47], v[106:109], v[114:117], v[32:47]
	v_mfma_f32_32x32x16_bf16 v[16:31], v[118:121], v[110:113], v[16:31]
	v_mfma_f32_32x32x16_bf16 v[48:63], v[118:121], v[114:117], v[48:63]
	ds_read_b128 v[106:109], v240 offset:96
	ds_read_b128 v[110:113], v241 offset:36960
	ds_read_b128 v[114:117], v241 offset:41568
	ds_read_b128 v[118:121], v240 offset:4704
	s_waitcnt lgkmcnt(4)
	v_mfma_f32_32x32x16_bf16 v[0:15], v[90:93], v[94:97], v[0:15]
	v_mfma_f32_32x32x16_bf16 v[32:47], v[90:93], v[98:101], v[32:47]
	v_mfma_f32_32x32x16_bf16 v[16:31], v[102:105], v[94:97], v[16:31]
	v_mfma_f32_32x32x16_bf16 v[48:63], v[102:105], v[98:101], v[48:63]
	s_waitcnt vmcnt(0)
	ds_write_b128 v242, v[192:195] offset:18432
	ds_write_b128 v242, v[196:199] offset:55296
	ds_write_b128 v243, v[200:203] offset:18432
	ds_write_b128 v243, v[204:207] offset:55296
	s_waitcnt lgkmcnt(4)
	v_mfma_f32_32x32x16_bf16 v[0:15], v[106:109], v[110:113], v[0:15]
	v_mfma_f32_32x32x16_bf16 v[32:47], v[106:109], v[114:117], v[32:47]
	ds_write_b128 v244, v[208:211] offset:18432
	ds_write_b128 v244, v[212:215] offset:55296
	ds_write_b128 v245, v[216:219] offset:18432
	ds_write_b128 v245, v[220:223] offset:55296
	v_mfma_f32_32x32x16_bf16 v[16:31], v[118:121], v[110:113], v[16:31]
	v_mfma_f32_32x32x16_bf16 v[48:63], v[118:121], v[114:117], v[48:63]
	s_waitcnt lgkmcnt(0)
	s_barrier
	ds_read_b128 v[90:93], v240 offset:18432
	ds_read_b128 v[94:97], v241 offset:55296
	ds_read_b128 v[98:101], v241 offset:59904
	ds_read_b128 v[102:105], v240 offset:23040
	ds_read_b128 v[106:109], v240 offset:18464
	ds_read_b128 v[110:113], v241 offset:55328
	ds_read_b128 v[114:117], v241 offset:59936
	ds_read_b128 v[118:121], v240 offset:23072
	s_waitcnt lgkmcnt(4)
	v_mfma_f32_32x32x16_bf16 v[0:15], v[90:93], v[94:97], v[0:15]
	v_mfma_f32_32x32x16_bf16 v[32:47], v[90:93], v[98:101], v[32:47]
	v_mfma_f32_32x32x16_bf16 v[16:31], v[102:105], v[94:97], v[16:31]
	v_mfma_f32_32x32x16_bf16 v[48:63], v[102:105], v[98:101], v[48:63]
	ds_read_b128 v[90:93], v240 offset:18496
	ds_read_b128 v[94:97], v241 offset:55360
	ds_read_b128 v[98:101], v241 offset:59968
	ds_read_b128 v[102:105], v240 offset:23104
	s_waitcnt lgkmcnt(4)
	v_mfma_f32_32x32x16_bf16 v[0:15], v[106:109], v[110:113], v[0:15]
	v_mfma_f32_32x32x16_bf16 v[32:47], v[106:109], v[114:117], v[32:47]
	v_mfma_f32_32x32x16_bf16 v[16:31], v[118:121], v[110:113], v[16:31]
	v_mfma_f32_32x32x16_bf16 v[48:63], v[118:121], v[114:117], v[48:63]
	ds_read_b128 v[106:109], v240 offset:18528
	ds_read_b128 v[110:113], v241 offset:55392
	ds_read_b128 v[114:117], v241 offset:60000
	ds_read_b128 v[118:121], v240 offset:23136
	s_waitcnt lgkmcnt(4)
	v_mfma_f32_32x32x16_bf16 v[0:15], v[90:93], v[94:97], v[0:15]
	v_mfma_f32_32x32x16_bf16 v[32:47], v[90:93], v[98:101], v[32:47]
	v_mfma_f32_32x32x16_bf16 v[16:31], v[102:105], v[94:97], v[16:31]
	v_mfma_f32_32x32x16_bf16 v[48:63], v[102:105], v[98:101], v[48:63]
	s_waitcnt lgkmcnt(0)
	s_barrier
	v_mfma_f32_32x32x16_bf16 v[0:15], v[106:109], v[110:113], v[0:15]
	v_mfma_f32_32x32x16_bf16 v[32:47], v[106:109], v[114:117], v[32:47]
	v_mfma_f32_32x32x16_bf16 v[16:31], v[118:121], v[110:113], v[16:31]
	v_mfma_f32_32x32x16_bf16 v[48:63], v[118:121], v[114:117], v[48:63]
	s_nop 15
	v_lshl_or_b32 v128, s46, 7, v80
	s_lshl_b32 s47, s47, 10
	s_mov_b32 s54, 0
	v_mov_b32_e32 v64, v133
	v_mov_b32_e32 v65, v133
	s_nop 0
	v_lshrrev_b32_e32 v65, 6, v65
	v_and_b32_e32 v66, 31, v64
	v_mul_lo_u32 v65, v65, s6
	v_lshrrev_b32_e32 v67, 3, v64
	v_and_b32_e32 v67, 4, v67
	v_lshl_or_b32 v66, v66, 2, v65
	v_mad_u32_u24 v66, v67, s7, v66
	s_nop 0
	ds_write2_b32 v66, v0, v32 offset1:32
	ds_write2_b32 v66, v1, v33 offset0:68 offset1:100
	ds_write2_b32 v66, v2, v34 offset0:136 offset1:168
	ds_write2_b32 v66, v3, v35 offset0:204 offset1:236
	v_add_u32_e32 v0, 0x800, v66
	ds_write2_b32 v0, v4, v36 offset0:32 offset1:64
	ds_write2_b32 v0, v5, v37 offset0:100 offset1:132
	ds_write2_b32 v0, v6, v38 offset0:168 offset1:200
	v_add_u32_e32 v0, 0xa00, v66
	ds_write2_b32 v0, v7, v39 offset0:108 offset1:140
	v_add_u32_e32 v0, 0x1000, v66
	ds_write2_b32 v0, v8, v40 offset0:64 offset1:96
	ds_write2_b32 v0, v9, v41 offset0:132 offset1:164
	ds_write2_b32 v0, v10, v42 offset0:200 offset1:232
	v_add_u32_e32 v0, 0x1400, v66
	ds_write2_b32 v0, v11, v43 offset0:12 offset1:44
	v_add_u32_e32 v0, 0x1800, v66
	ds_write2_b32 v0, v12, v44 offset0:96 offset1:128
	ds_write2_b32 v0, v13, v45 offset0:164 offset1:196
	v_add_u32_e32 v0, 0x1a00, v66
	ds_write2_b32 v0, v14, v46 offset0:104 offset1:136
	v_add_u32_e32 v0, 0x1c00, v66
	ds_write2_b32 v0, v15, v47 offset0:44 offset1:76
	v_add_u32_e32 v0, 0x2000, v66
	s_nop 1
	ds_write2_b32 v0, v16, v48 offset0:128 offset1:160
	ds_write2_b32 v0, v17, v49 offset0:196 offset1:228
	v_add_u32_e32 v0, 0x2400, v66
	ds_write2_b32 v0, v18, v50 offset0:8 offset1:40
	ds_write2_b32 v0, v19, v51 offset0:76 offset1:108
	v_add_u32_e32 v0, 0x2800, v66
	ds_write2_b32 v0, v20, v52 offset0:160 offset1:192
	v_add_u32_e32 v0, 0x2a00, v66
	ds_write2_b32 v0, v21, v53 offset0:100 offset1:132
	v_add_u32_e32 v0, 0x2c00, v66
	ds_write2_b32 v0, v22, v54 offset0:40 offset1:72
	ds_write2_b32 v0, v23, v55 offset0:108 offset1:140
	v_add_u32_e32 v0, 0x3000, v66
	ds_write2_b32 v0, v24, v56 offset0:192 offset1:224
	v_add_u32_e32 v0, 0x3400, v66
	ds_write2_b32 v0, v25, v57 offset0:4 offset1:36
	ds_write2_b32 v0, v26, v58 offset0:72 offset1:104
	ds_write2_b32 v0, v27, v59 offset0:140 offset1:172
	v_add_u32_e32 v0, 0x3a00, v66
	ds_write2_b32 v0, v28, v60 offset0:96 offset1:128
	v_add_u32_e32 v0, 0x3c00, v66
	ds_write2_b32 v0, v29, v61 offset0:36 offset1:68
	ds_write2_b32 v0, v30, v62 offset0:104 offset1:136
	ds_write2_b32 v0, v31, v63 offset0:172 offset1:204
	v_lshlrev_b32_e32 v0, 3, v64
	v_and_b32_e32 v2, 56, v0
	v_lshl_add_u64 v[0:1], s[44:45], 0, v[128:129]
	v_lshlrev_b32_e32 v128, 1, v2
	v_bfe_u32 v3, v64, 3, 3
	v_lshl_add_u64 v[12:13], v[0:1], 0, v[128:129]
	v_and_b32_e32 v1, 7, v64
	v_mul_u32_u24_e32 v0, 0x110, v3
	v_lshlrev_b32_e32 v1, 5, v1
	v_cmp_gt_u32_e64 s[42:43], 32, v2
	v_add3_u32 v14, v82, s47, v3
	v_add3_u32 v16, v65, v0, v1
	s_branch .LBB0_787

.LBB0_857:
	s_bfe_u32 s57, s54, 0x60003
	s_lshl_b32 s48, s57, 21
	s_or_b32 s60, s1, s48
	s_and_b32 s48, s53, 7
	s_lshl_b32 s61, s48, 18
	s_and_b32 s48, s54, 0x1f8
	s_or_b32 s55, s48, s33
	s_and_b32 s56, s54, 7
	s_lshl_b32 s48, s55, 18
	s_add_u32 s48, s30, s48
	v_mov_b32_e32 v48, v133
	s_addc_u32 s49, s38, 0
	s_lshl_b32 s58, s56, 18
	s_add_u32 s58, s2, s58
	v_add_u32_e32 v8, 0x100, v48
	v_add_u32_e32 v16, 0x200, v48
	v_add_u32_e32 v28, 0x300, v48
	v_lshlrev_b32_e32 v0, 4, v48
	v_ashrrev_i32_e32 v32, 3, v48
	v_ashrrev_i32_e32 v36, 3, v8
	v_ashrrev_i32_e32 v40, 3, v16
	v_ashrrev_i32_e32 v44, 3, v28
	s_addc_u32 s59, s3, 0
	v_and_b32_e32 v128, 0x70, v0
	v_ashrrev_i32_e32 v33, 31, v32
	v_ashrrev_i32_e32 v37, 31, v36
	v_ashrrev_i32_e32 v41, 31, v40
	v_ashrrev_i32_e32 v45, 31, v44
	v_lshl_add_u64 v[24:25], s[48:49], 0, v[128:129]
	v_lshl_add_u64 v[26:27], s[58:59], 0, v[128:129]
	v_lshlrev_b64 v[34:35], 11, v[32:33]
	v_lshlrev_b64 v[38:39], 11, v[36:37]
	v_lshlrev_b64 v[42:43], 11, v[40:41]
	v_lshlrev_b64 v[46:47], 11, v[44:45]
	v_lshl_add_u64 v[0:1], v[24:25], 0, v[34:35]
	v_lshl_add_u64 v[4:5], v[26:27], 0, v[34:35]
	v_lshl_add_u64 v[8:9], v[24:25], 0, v[38:39]
	v_lshl_add_u64 v[12:13], v[26:27], 0, v[38:39]
	v_lshl_add_u64 v[16:17], v[24:25], 0, v[42:43]
	v_lshl_add_u64 v[20:21], v[26:27], 0, v[42:43]
	v_lshl_add_u64 v[24:25], v[24:25], 0, v[46:47]
	v_lshl_add_u64 v[28:29], v[26:27], 0, v[46:47]
	global_load_dwordx4 v[0:3], v[0:1], off
	s_nop 0
	global_load_dwordx4 v[4:7], v[4:5], off
	s_nop 0
	global_load_dwordx4 v[8:11], v[8:9], off
	s_nop 0
	global_load_dwordx4 v[12:15], v[12:13], off
	s_nop 0
	global_load_dwordx4 v[16:19], v[16:17], off
	s_nop 0
	global_load_dwordx4 v[20:23], v[20:21], off
	s_nop 0
	global_load_dwordx4 v[24:27], v[24:25], off
	s_nop 0
	global_load_dwordx4 v[28:31], v[28:29], off
	s_add_u32 s48, s39, s60
	v_and_b32_e32 v33, 31, v48
	v_lshrrev_b32_e32 v37, 1, v48
	v_mul_lo_u32 v84, v32, s85
	v_or_b32_e32 v34, v34, v128
	s_addc_u32 s49, s50, 0
	v_or_b32_e32 v38, v38, v128
	v_or_b32_e32 v42, v42, v128
	v_or_b32_e32 v46, v46, v128
	v_or_b32_e32 v32, v33, v81
	v_and_b32_e32 v83, 16, v37
	v_or_b32_e32 v33, v33, v80
	v_add_u32_e32 v37, v128, v84
	v_mul_lo_u32 v87, v36, s85
	s_waitcnt vmcnt(16)
	v_mul_lo_u32 v88, v40, s85
	s_waitcnt vmcnt(9)
	v_mul_lo_u32 v89, v44, s85
	v_lshl_add_u64 v[64:65], s[48:49], 0, v[34:35]
	v_lshl_add_u64 v[66:67], s[48:49], 0, v[38:39]
	v_lshl_add_u64 v[68:69], s[48:49], 0, v[42:43]
	v_lshl_add_u64 v[70:71], s[48:49], 0, v[46:47]
	s_add_u32 s48, s51, s61
	v_mul_lo_u32 v85, v32, s85
	v_mul_u32_u24_e32 v86, 0x90, v33
	v_add_u32_e32 v32, v128, v87
	v_add_u32_e32 v33, v128, v88
	v_add_u32_e32 v36, v128, v89
	s_addc_u32 s49, s52, 0
	v_lshl_add_u64 v[72:73], s[48:49], 0, v[34:35]
	v_lshl_add_u64 v[74:75], s[48:49], 0, v[38:39]
	v_lshl_add_u64 v[76:77], s[48:49], 0, v[42:43]
	v_lshl_add_u64 v[78:79], s[48:49], 0, v[46:47]
	s_mov_b32 s58, 0
	s_mov_b64 s[48:49], 0
	global_load_dwordx4 v[192:195], v[64:65], off
	global_load_dwordx4 v[196:199], v[72:73], off
	global_load_dwordx4 v[200:203], v[66:67], off
	global_load_dwordx4 v[204:207], v[74:75], off
	global_load_dwordx4 v[208:211], v[68:69], off
	global_load_dwordx4 v[212:215], v[76:77], off
	global_load_dwordx4 v[216:219], v[70:71], off
	global_load_dwordx4 v[220:223], v[78:79], off
	s_waitcnt vmcnt(15)
	ds_write_b128 v37, v[0:3]
	s_waitcnt vmcnt(14)
	ds_write_b128 v37, v[4:7] offset:36864
	s_waitcnt vmcnt(13)
	ds_write_b128 v32, v[8:11]
	s_waitcnt vmcnt(12)
	ds_write_b128 v32, v[12:15] offset:36864
	s_waitcnt vmcnt(11)
	ds_write_b128 v33, v[16:19]
	s_waitcnt vmcnt(10)
	ds_write_b128 v33, v[20:23] offset:36864
	s_waitcnt vmcnt(9)
	ds_write_b128 v36, v[24:27]
	s_waitcnt vmcnt(8)
	ds_write_b128 v36, v[28:31] offset:36864
	v_mov_b32_e32 v0, 0
	v_mov_b32_e32 v1, v0
	v_mov_b32_e32 v2, v0
	v_mov_b32_e32 v3, v0
	v_mov_b32_e32 v4, v0
	v_mov_b32_e32 v5, v0
	v_mov_b32_e32 v6, v0
	v_mov_b32_e32 v7, v0
	v_mov_b32_e32 v8, v0
	v_mov_b32_e32 v9, v0
	v_mov_b32_e32 v10, v0
	v_mov_b32_e32 v11, v0
	v_mov_b32_e32 v12, v0
	v_mov_b32_e32 v13, v0
	v_mov_b32_e32 v14, v0
	v_mov_b32_e32 v15, v0
	v_mov_b32_e32 v32, v0
	v_mov_b32_e32 v33, v0
	v_mov_b32_e32 v34, v0
	v_mov_b32_e32 v35, v0
	v_mov_b32_e32 v36, v0
	v_mov_b32_e32 v37, v0
	v_mov_b32_e32 v38, v0
	v_mov_b32_e32 v39, v0
	v_mov_b32_e32 v40, v0
	v_mov_b32_e32 v41, v0
	v_mov_b32_e32 v42, v0
	v_mov_b32_e32 v43, v0
	v_mov_b32_e32 v44, v0
	v_mov_b32_e32 v45, v0
	v_mov_b32_e32 v46, v0
	v_mov_b32_e32 v47, v0
	v_mov_b32_e32 v16, v0
	v_mov_b32_e32 v17, v0
	v_mov_b32_e32 v18, v0
	v_mov_b32_e32 v19, v0
	v_mov_b32_e32 v20, v0
	v_mov_b32_e32 v21, v0
	v_mov_b32_e32 v22, v0
	v_mov_b32_e32 v23, v0
	v_mov_b32_e32 v24, v0
	v_mov_b32_e32 v25, v0
	v_mov_b32_e32 v26, v0
	v_mov_b32_e32 v27, v0
	v_mov_b32_e32 v28, v0
	v_mov_b32_e32 v29, v0
	v_mov_b32_e32 v30, v0
	v_mov_b32_e32 v31, v0
	v_mov_b32_e32 v48, v0
	v_mov_b32_e32 v49, v0
	v_mov_b32_e32 v50, v0
	v_mov_b32_e32 v51, v0
	v_mov_b32_e32 v52, v0
	v_mov_b32_e32 v53, v0
	v_mov_b32_e32 v54, v0
	v_mov_b32_e32 v55, v0
	v_mov_b32_e32 v56, v0
	v_mov_b32_e32 v57, v0
	v_mov_b32_e32 v58, v0
	v_mov_b32_e32 v59, v0
	v_mov_b32_e32 v60, v0
	v_mov_b32_e32 v61, v0
	v_mov_b32_e32 v62, v0
	v_mov_b32_e32 v63, v0
	s_waitcnt lgkmcnt(0)
	s_barrier
	v_add_u32_e32 v240, v85, v83
	v_add_u32_e32 v241, v86, v83
	v_add_u32_e32 v242, v128, v84
	v_add_u32_e32 v243, v128, v87
	v_add_u32_e32 v244, v128, v88
	v_add_u32_e32 v245, v128, v89
.Lmm_wout_loop:
	ds_read_b128 v[90:93], v240
	ds_read_b128 v[94:97], v241 offset:36864
	ds_read_b128 v[98:101], v241 offset:41472
	ds_read_b128 v[102:105], v240 offset:4608
	v_lshl_add_u64 v[224:225], v[64:65], 0, s[48:49]
	v_lshl_add_u64 v[226:227], v[72:73], 0, s[48:49]
	v_lshl_add_u64 v[228:229], v[66:67], 0, s[48:49]
	v_lshl_add_u64 v[230:231], v[74:75], 0, s[48:49]
	v_lshl_add_u64 v[232:233], v[68:69], 0, s[48:49]
	v_lshl_add_u64 v[234:235], v[76:77], 0, s[48:49]
	v_lshl_add_u64 v[236:237], v[70:71], 0, s[48:49]
	v_lshl_add_u64 v[238:239], v[78:79], 0, s[48:49]
	global_load_dwordx4 v[142:145], v[224:225], off offset:128
	global_load_dwordx4 v[146:149], v[226:227], off offset:128
	global_load_dwordx4 v[150:153], v[228:229], off offset:128
	global_load_dwordx4 v[154:157], v[230:231], off offset:128
	global_load_dwordx4 v[158:161], v[232:233], off offset:128
	global_load_dwordx4 v[162:165], v[234:235], off offset:128
	global_load_dwordx4 v[166:169], v[236:237], off offset:128
	global_load_dwordx4 v[170:173], v[238:239], off offset:128
	ds_read_b128 v[106:109], v240 offset:32
	ds_read_b128 v[110:113], v241 offset:36896
	ds_read_b128 v[114:117], v241 offset:41504
	ds_read_b128 v[118:121], v240 offset:4640
	s_waitcnt lgkmcnt(4)
	v_mfma_f32_32x32x16_bf16 v[0:15], v[90:93], v[94:97], v[0:15]
	v_mfma_f32_32x32x16_bf16 v[32:47], v[90:93], v[98:101], v[32:47]
	v_mfma_f32_32x32x16_bf16 v[16:31], v[102:105], v[94:97], v[16:31]
	v_mfma_f32_32x32x16_bf16 v[48:63], v[102:105], v[98:101], v[48:63]
	ds_read_b128 v[90:93], v240 offset:64
	ds_read_b128 v[94:97], v241 offset:36928
	ds_read_b128 v[98:101], v241 offset:41536
	ds_read_b128 v[102:105], v240 offset:4672
	s_waitcnt lgkmcnt(4)
	v_mfma_f32_32x32x16_bf16 v[0:15], v[106:109], v[110:113], v[0:15]
	v_mfma_f32_32x32x16_bf16 v[32:47], v[106:109], v[114:117], v[32:47]
	v_mfma_f32_32x32x16_bf16 v[16:31], v[118:121], v[110:113], v[16:31]
	v_mfma_f32_32x32x16_bf16 v[48:63], v[118:121], v[114:117], v[48:63]
	ds_read_b128 v[106:109], v240 offset:96
	ds_read_b128 v[110:113], v241 offset:36960
	ds_read_b128 v[114:117], v241 offset:41568
	ds_read_b128 v[118:121], v240 offset:4704
	s_waitcnt lgkmcnt(4)
	v_mfma_f32_32x32x16_bf16 v[0:15], v[90:93], v[94:97], v[0:15]
	v_mfma_f32_32x32x16_bf16 v[32:47], v[90:93], v[98:101], v[32:47]
	v_mfma_f32_32x32x16_bf16 v[16:31], v[102:105], v[94:97], v[16:31]
	v_mfma_f32_32x32x16_bf16 v[48:63], v[102:105], v[98:101], v[48:63]
	s_add_u32 s48, s48, 0x80
	s_addc_u32 s49, s49, 0
	s_waitcnt vmcnt(8)
	ds_write_b128 v242, v[192:195] offset:18432
	ds_write_b128 v242, v[196:199] offset:55296
	ds_write_b128 v243, v[200:203] offset:18432
	ds_write_b128 v243, v[204:207] offset:55296
	s_waitcnt lgkmcnt(4)
	v_mfma_f32_32x32x16_bf16 v[0:15], v[106:109], v[110:113], v[0:15]
	v_mfma_f32_32x32x16_bf16 v[32:47], v[106:109], v[114:117], v[32:47]
	ds_write_b128 v244, v[208:211] offset:18432
	ds_write_b128 v244, v[212:215] offset:55296
	ds_write_b128 v245, v[216:219] offset:18432
	ds_write_b128 v245, v[220:223] offset:55296
	v_mfma_f32_32x32x16_bf16 v[16:31], v[118:121], v[110:113], v[16:31]
	v_mfma_f32_32x32x16_bf16 v[48:63], v[118:121], v[114:117], v[48:63]
	s_waitcnt lgkmcnt(0)
	s_barrier
	ds_read_b128 v[90:93], v240 offset:18432
	ds_read_b128 v[94:97], v241 offset:55296
	ds_read_b128 v[98:101], v241 offset:59904
	ds_read_b128 v[102:105], v240 offset:23040
	v_lshl_add_u64 v[224:225], v[64:65], 0, s[48:49]
	v_lshl_add_u64 v[226:227], v[72:73], 0, s[48:49]
	v_lshl_add_u64 v[228:229], v[66:67], 0, s[48:49]
	v_lshl_add_u64 v[230:231], v[74:75], 0, s[48:49]
	v_lshl_add_u64 v[232:233], v[68:69], 0, s[48:49]
	v_lshl_add_u64 v[234:235], v[76:77], 0, s[48:49]
	v_lshl_add_u64 v[236:237], v[70:71], 0, s[48:49]
	v_lshl_add_u64 v[238:239], v[78:79], 0, s[48:49]
	global_load_dwordx4 v[192:195], v[224:225], off offset:128
	global_load_dwordx4 v[196:199], v[226:227], off offset:128
	global_load_dwordx4 v[200:203], v[228:229], off offset:128
	global_load_dwordx4 v[204:207], v[230:231], off offset:128
	global_load_dwordx4 v[208:211], v[232:233], off offset:128
	global_load_dwordx4 v[212:215], v[234:235], off offset:128
	global_load_dwordx4 v[216:219], v[236:237], off offset:128
	global_load_dwordx4 v[220:223], v[238:239], off offset:128
	ds_read_b128 v[106:109], v240 offset:18464
	ds_read_b128 v[110:113], v241 offset:55328
	ds_read_b128 v[114:117], v241 offset:59936
	ds_read_b128 v[118:121], v240 offset:23072
	s_waitcnt lgkmcnt(4)
	v_mfma_f32_32x32x16_bf16 v[0:15], v[90:93], v[94:97], v[0:15]
	v_mfma_f32_32x32x16_bf16 v[32:47], v[90:93], v[98:101], v[32:47]
	v_mfma_f32_32x32x16_bf16 v[16:31], v[102:105], v[94:97], v[16:31]
	v_mfma_f32_32x32x16_bf16 v[48:63], v[102:105], v[98:101], v[48:63]
	ds_read_b128 v[90:93], v240 offset:18496
	ds_read_b128 v[94:97], v241 offset:55360
	ds_read_b128 v[98:101], v241 offset:59968
	ds_read_b128 v[102:105], v240 offset:23104
	s_waitcnt lgkmcnt(4)
	v_mfma_f32_32x32x16_bf16 v[0:15], v[106:109], v[110:113], v[0:15]
	v_mfma_f32_32x32x16_bf16 v[32:47], v[106:109], v[114:117], v[32:47]
	v_mfma_f32_32x32x16_bf16 v[16:31], v[118:121], v[110:113], v[16:31]
	v_mfma_f32_32x32x16_bf16 v[48:63], v[118:121], v[114:117], v[48:63]
	ds_read_b128 v[106:109], v240 offset:18528
	ds_read_b128 v[110:113], v241 offset:55392
	ds_read_b128 v[114:117], v241 offset:60000
	ds_read_b128 v[118:121], v240 offset:23136
	s_waitcnt lgkmcnt(4)
	v_mfma_f32_32x32x16_bf16 v[0:15], v[90:93], v[94:97], v[0:15]
	v_mfma_f32_32x32x16_bf16 v[32:47], v[90:93], v[98:101], v[32:47]
	v_mfma_f32_32x32x16_bf16 v[16:31], v[102:105], v[94:97], v[16:31]
	v_mfma_f32_32x32x16_bf16 v[48:63], v[102:105], v[98:101], v[48:63]
	s_add_u32 s48, s48, 0x80
	s_addc_u32 s49, s49, 0
	s_waitcnt vmcnt(8)
	ds_write_b128 v242, v[142:145]
	ds_write_b128 v242, v[146:149] offset:36864
	ds_write_b128 v243, v[150:153]
	ds_write_b128 v243, v[154:157] offset:36864
	s_waitcnt lgkmcnt(4)
	v_mfma_f32_32x32x16_bf16 v[0:15], v[106:109], v[110:113], v[0:15]
	v_mfma_f32_32x32x16_bf16 v[32:47], v[106:109], v[114:117], v[32:47]
	ds_write_b128 v244, v[158:161]
	ds_write_b128 v244, v[162:165] offset:36864
	ds_write_b128 v245, v[166:169]
	ds_write_b128 v245, v[170:173] offset:36864
	v_mfma_f32_32x32x16_bf16 v[16:31], v[118:121], v[110:113], v[16:31]
	v_mfma_f32_32x32x16_bf16 v[48:63], v[118:121], v[114:117], v[48:63]
	s_waitcnt lgkmcnt(0)
	s_barrier
	s_cmpk_lg_i32 s48, 0x700
	s_cbranch_scc1 .Lmm_wout_loop
	ds_read_b128 v[90:93], v240
	ds_read_b128 v[94:97], v241 offset:36864
	ds_read_b128 v[98:101], v241 offset:41472
	ds_read_b128 v[102:105], v240 offset:4608
	ds_read_b128 v[106:109], v240 offset:32
	ds_read_b128 v[110:113], v241 offset:36896
	ds_read_b128 v[114:117], v241 offset:41504
	ds_read_b128 v[118:121], v240 offset:4640
	s_waitcnt lgkmcnt(4)
	v_mfma_f32_32x32x16_bf16 v[0:15], v[90:93], v[94:97], v[0:15]
	v_mfma_f32_32x32x16_bf16 v[32:47], v[90:93], v[98:101], v[32:47]
	v_mfma_f32_32x32x16_bf16 v[16:31], v[102:105], v[94:97], v[16:31]
	v_mfma_f32_32x32x16_bf16 v[48:63], v[102:105], v[98:101], v[48:63]
	ds_read_b128 v[90:93], v240 offset:64
	ds_read_b128 v[94:97], v241 offset:36928
	ds_read_b128 v[98:101], v241 offset:41536
	ds_read_b128 v[102:105], v240 offset:4672
	s_waitcnt lgkmcnt(4)
	v_mfma_f32_32x32x16_bf16 v[0:15], v[106:109], v[110:113], v[0:15]
	v_mfma_f32_32x32x16_bf16 v[32:47], v[106:109], v[114:117], v[32:47]
	v_mfma_f32_32x32x16_bf16 v[16:31], v[118:121], v[110:113], v[16:31]
	v_mfma_f32_32x32x16_bf16 v[48:63], v[118:121], v[114:117], v[48:63]
	ds_read_b128 v[106:109], v240 offset:96
	ds_read_b128 v[110:113], v241 offset:36960
	ds_read_b128 v[114:117], v241 offset:41568
	ds_read_b128 v[118:121], v240 offset:4704
	s_waitcnt lgkmcnt(4)
	v_mfma_f32_32x32x16_bf16 v[0:15], v[90:93], v[94:97], v[0:15]
	v_mfma_f32_32x32x16_bf16 v[32:47], v[90:93], v[98:101], v[32:47]
	v_mfma_f32_32x32x16_bf16 v[16:31], v[102:105], v[94:97], v[16:31]
	v_mfma_f32_32x32x16_bf16 v[48:63], v[102:105], v[98:101], v[48:63]
	s_waitcnt vmcnt(0)
	ds_write_b128 v242, v[192:195] offset:18432
	ds_write_b128 v242, v[196:199] offset:55296
	ds_write_b128 v243, v[200:203] offset:18432
	ds_write_b128 v243, v[204:207] offset:55296
	s_waitcnt lgkmcnt(4)
	v_mfma_f32_32x32x16_bf16 v[0:15], v[106:109], v[110:113], v[0:15]
	v_mfma_f32_32x32x16_bf16 v[32:47], v[106:109], v[114:117], v[32:47]
	ds_write_b128 v244, v[208:211] offset:18432
	ds_write_b128 v244, v[212:215] offset:55296
	ds_write_b128 v245, v[216:219] offset:18432
	ds_write_b128 v245, v[220:223] offset:55296
	v_mfma_f32_32x32x16_bf16 v[16:31], v[118:121], v[110:113], v[16:31]
	v_mfma_f32_32x32x16_bf16 v[48:63], v[118:121], v[114:117], v[48:63]
	s_waitcnt lgkmcnt(0)
	s_barrier
	ds_read_b128 v[90:93], v240 offset:18432
	ds_read_b128 v[94:97], v241 offset:55296
	ds_read_b128 v[98:101], v241 offset:59904
	ds_read_b128 v[102:105], v240 offset:23040
	ds_read_b128 v[106:109], v240 offset:18464
	ds_read_b128 v[110:113], v241 offset:55328
	ds_read_b128 v[114:117], v241 offset:59936
	ds_read_b128 v[118:121], v240 offset:23072
	s_waitcnt lgkmcnt(4)
	v_mfma_f32_32x32x16_bf16 v[0:15], v[90:93], v[94:97], v[0:15]
	v_mfma_f32_32x32x16_bf16 v[32:47], v[90:93], v[98:101], v[32:47]
	v_mfma_f32_32x32x16_bf16 v[16:31], v[102:105], v[94:97], v[16:31]
	v_mfma_f32_32x32x16_bf16 v[48:63], v[102:105], v[98:101], v[48:63]
	ds_read_b128 v[90:93], v240 offset:18496
	ds_read_b128 v[94:97], v241 offset:55360
	ds_read_b128 v[98:101], v241 offset:59968
	ds_read_b128 v[102:105], v240 offset:23104
	s_waitcnt lgkmcnt(4)
	v_mfma_f32_32x32x16_bf16 v[0:15], v[106:109], v[110:113], v[0:15]
	v_mfma_f32_32x32x16_bf16 v[32:47], v[106:109], v[114:117], v[32:47]
	v_mfma_f32_32x32x16_bf16 v[16:31], v[118:121], v[110:113], v[16:31]
	v_mfma_f32_32x32x16_bf16 v[48:63], v[118:121], v[114:117], v[48:63]
	ds_read_b128 v[106:109], v240 offset:18528
	ds_read_b128 v[110:113], v241 offset:55392
	ds_read_b128 v[114:117], v241 offset:60000
	ds_read_b128 v[118:121], v240 offset:23136
	s_waitcnt lgkmcnt(4)
	v_mfma_f32_32x32x16_bf16 v[0:15], v[90:93], v[94:97], v[0:15]
	v_mfma_f32_32x32x16_bf16 v[32:47], v[90:93], v[98:101], v[32:47]
	v_mfma_f32_32x32x16_bf16 v[16:31], v[102:105], v[94:97], v[16:31]
	v_mfma_f32_32x32x16_bf16 v[48:63], v[102:105], v[98:101], v[48:63]
	s_waitcnt lgkmcnt(0)
	s_barrier
	v_mfma_f32_32x32x16_bf16 v[0:15], v[106:109], v[110:113], v[0:15]
	v_mfma_f32_32x32x16_bf16 v[32:47], v[106:109], v[114:117], v[32:47]
	v_mfma_f32_32x32x16_bf16 v[16:31], v[118:121], v[110:113], v[16:31]
	v_mfma_f32_32x32x16_bf16 v[48:63], v[118:121], v[114:117], v[48:63]
	s_nop 15
	s_lshl_b32 s49, s57, 10
	s_mov_b32 s48, 0
	v_lshl_add_u32 v64, s55, 7, v81
	v_add_u32_e32 v65, 0xffffe000, v64
	v_lshrrev_b32_e32 v65, 12, v65
	v_add_u32_e32 v65, 1, v65
	v_cmp_lt_i32_e32 vcc, s22, v64
	v_lshl_or_b32 v66, s56, 7, v80
	v_lshlrev_b32_e32 v128, 2, v66
	v_cndmask_b32_e32 v67, 0, v65, vcc
	v_mov_b64_e32 v[64:65], s[44:45]
	v_mad_u64_u32 v[64:65], s[56:57], v67, s23, v[64:65]
	v_mov_b32_e32 v67, v133
	v_lshl_add_u64 v[64:65], v[64:65], 0, v[128:129]
	s_mov_b64 s[56:57], 0x13402000
	v_mov_b32_e32 v68, v133
	v_and_b32_e32 v69, 31, v67
	v_lshrrev_b32_e32 v68, 6, v68
	v_mul_lo_u32 v68, v68, s6
	v_lshrrev_b32_e32 v70, 3, v67
	v_and_b32_e32 v70, 4, v70
	v_lshl_or_b32 v69, v69, 2, v68
	v_mad_u32_u24 v69, v70, s7, v69
	ds_write2_b32 v69, v0, v32 offset1:32
	ds_write2_b32 v69, v1, v33 offset0:68 offset1:100
	ds_write2_b32 v69, v2, v34 offset0:136 offset1:168
	ds_write2_b32 v69, v3, v35 offset0:204 offset1:236
	v_add_u32_e32 v0, 0x800, v69
	ds_write2_b32 v0, v4, v36 offset0:32 offset1:64
	ds_write2_b32 v0, v5, v37 offset0:100 offset1:132
	ds_write2_b32 v0, v6, v38 offset0:168 offset1:200
	v_add_u32_e32 v0, 0xa00, v69
	ds_write2_b32 v0, v7, v39 offset0:108 offset1:140
	v_add_u32_e32 v0, 0x1000, v69
	ds_write2_b32 v0, v8, v40 offset0:64 offset1:96
	ds_write2_b32 v0, v9, v41 offset0:132 offset1:164
	ds_write2_b32 v0, v10, v42 offset0:200 offset1:232
	v_add_u32_e32 v0, 0x1400, v69
	ds_write2_b32 v0, v11, v43 offset0:12 offset1:44
	v_add_u32_e32 v0, 0x1800, v69
	ds_write2_b32 v0, v12, v44 offset0:96 offset1:128
	ds_write2_b32 v0, v13, v45 offset0:164 offset1:196
	v_add_u32_e32 v0, 0x1a00, v69
	ds_write2_b32 v0, v14, v46 offset0:104 offset1:136
	v_add_u32_e32 v0, 0x1c00, v69
	ds_write2_b32 v0, v15, v47 offset0:44 offset1:76
	v_add_u32_e32 v0, 0x2000, v69
	ds_write2_b32 v0, v16, v48 offset0:128 offset1:160
	ds_write2_b32 v0, v17, v49 offset0:196 offset1:228
	v_add_u32_e32 v0, 0x2400, v69
	ds_write2_b32 v0, v18, v50 offset0:8 offset1:40
	ds_write2_b32 v0, v19, v51 offset0:76 offset1:108
	v_add_u32_e32 v0, 0x2800, v69
	ds_write2_b32 v0, v20, v52 offset0:160 offset1:192
	v_add_u32_e32 v0, 0x2a00, v69
	ds_write2_b32 v0, v21, v53 offset0:100 offset1:132
	v_add_u32_e32 v0, 0x2c00, v69
	ds_write2_b32 v0, v22, v54 offset0:40 offset1:72
	ds_write2_b32 v0, v23, v55 offset0:108 offset1:140
	v_add_u32_e32 v0, 0x3000, v69
	ds_write2_b32 v0, v24, v56 offset0:192 offset1:224
	v_add_u32_e32 v0, 0x3400, v69
	ds_write2_b32 v0, v25, v57 offset0:4 offset1:36
	ds_write2_b32 v0, v26, v58 offset0:72 offset1:104
	ds_write2_b32 v0, v27, v59 offset0:140 offset1:172
	v_add_u32_e32 v0, 0x3a00, v69
	ds_write2_b32 v0, v28, v60 offset0:96 offset1:128
	v_add_u32_e32 v0, 0x3c00, v69
	ds_write2_b32 v0, v29, v61 offset0:36 offset1:68
	ds_write2_b32 v0, v30, v62 offset0:104 offset1:136
	ds_write2_b32 v0, v31, v63 offset0:172 offset1:204
	v_lshlrev_b32_e32 v0, 3, v67
	v_and_b32_e32 v3, 56, v0
	v_lshlrev_b32_e32 v128, 2, v3
	v_lshl_add_u64 v[0:1], v[64:65], 0, v[128:129]
	v_lshlrev_b32_e32 v128, 1, v66
	v_lshl_add_u64 v[8:9], v[0:1], 0, s[56:57]
	v_lshl_add_u64 v[0:1], s[46:47], 0, v[128:129]
	v_lshlrev_b32_e32 v128, 1, v3
	v_bfe_u32 v2, v67, 3, 3
	v_lshl_add_u64 v[10:11], v[0:1], 0, v[128:129]
	v_and_b32_e32 v1, 7, v67
	v_mul_u32_u24_e32 v0, 0x110, v2
	v_lshlrev_b32_e32 v1, 5, v1
	v_add3_u32 v12, v82, s49, v2
	v_add3_u32 v14, v68, v0, v1

.LBB0_1090:
	s_or_b64 exec, exec, s[78:79]
	v_lshlrev_b32_e32 v72, 16, v4
	v_and_b32_e32 v74, 0xffff0000, v4
	v_add_f32_e32 v73, v72, v72
	v_add_f32_e32 v4, v74, v74
	v_mov_b32_e32 v75, v129
	v_cvt_scalef32_pk_fp4_f32 v75, v73, v4, 1.0
	v_lshlrev_b32_e32 v73, 16, v5
	v_and_b32_e32 v76, 0xffff0000, v5
	v_add_f32_e32 v4, v73, v73
	v_add_f32_e32 v5, v76, v76
	v_lshlrev_b32_e32 v77, 16, v6
	v_and_b32_e32 v6, 0xffff0000, v6
	v_cvt_scalef32_pk_fp4_f32 v75, v4, v5, 1.0 op_sel:[0,0,1,0]
	v_add_f32_e32 v4, v77, v77
	v_add_f32_e32 v5, v6, v6
	v_lshlrev_b32_e32 v78, 16, v7
	v_and_b32_e32 v7, 0xffff0000, v7
	v_cvt_scalef32_pk_fp4_f32 v75, v4, v5, 1.0 op_sel:[0,0,0,1]
	v_add_f32_e32 v4, v78, v78
	v_add_f32_e32 v5, v7, v7
	v_cvt_scalef32_pk_fp4_f32 v75, v4, v5, 1.0 op_sel:[0,0,1,1]
	s_nop 0
	v_cvt_scalef32_pk_f32_fp4 v[4:5], v75, 1.0
	v_fma_f32 v5, v74, 2.0, -v5
	v_fma_f32 v4, v72, 2.0, -v4
	v_mul_f32_e32 v5, 4.0, v5
	v_mul_f32_e32 v4, 4.0, v4
	v_mov_b32_e32 v72, v129
	v_cvt_scalef32_pk_fp4_f32 v72, v4, v5, 1.0
	v_cvt_scalef32_pk_f32_fp4 v[4:5], v75, 1.0 op_sel:[1,0,0]
	v_fma_f32 v5, v76, 2.0, -v5
	v_fma_f32 v4, v73, 2.0, -v4
	v_mul_f32_e32 v5, 4.0, v5
	v_mul_f32_e32 v4, 4.0, v4
	v_cvt_scalef32_pk_fp4_f32 v72, v4, v5, 1.0 op_sel:[0,0,1,0]
	v_cvt_scalef32_pk_f32_fp4 v[4:5], v75, 1.0 op_sel:[0,1,0]
	v_fma_f32 v5, v6, 2.0, -v5
	v_fma_f32 v4, v77, 2.0, -v4
	v_mul_f32_e32 v5, 4.0, v5
	v_mul_f32_e32 v4, 4.0, v4
	v_cvt_scalef32_pk_fp4_f32 v72, v4, v5, 1.0 op_sel:[0,0,0,1]
	v_cvt_scalef32_pk_f32_fp4 v[4:5], v75, 1.0 op_sel:[1,1,0]
	v_fma_f32 v4, v78, 2.0, -v4
	v_fma_f32 v5, v7, 2.0, -v5
	v_mul_f32_e32 v4, 4.0, v4
	v_mul_f32_e32 v5, 4.0, v5
	v_cvt_scalef32_pk_fp4_f32 v72, v4, v5, 1.0 op_sel:[0,0,1,1]
	s_nop 0
	v_cndmask_b32_e64 v4, v72, v75, s[46:47]
	ds_write_b32 v85, v4 offset:17408
	ds_read_b128 v[72:75], v117 offset:17408
	ds_read_b128 v[4:7], v117 offset:17424
	ds_read_b128 v[80:83], v117 offset:17440
	ds_read_b128 v[76:79], v117 offset:17456
	s_waitcnt vmcnt(15)
	ds_write2_b64 v120, v[8:9], v[10:11] offset1:1
	s_waitcnt vmcnt(14)
	ds_write2_b64 v121, v[12:13], v[14:15] offset0:136 offset1:137
	v_add_u32_e32 v8, 0x880, v121
	s_waitcnt vmcnt(13)
	ds_write2_b64 v8, v[20:21], v[22:23] offset1:1
	v_add_u32_e32 v8, 0xcc0, v121
	s_waitcnt vmcnt(12)
	ds_write2_b64 v8, v[16:17], v[18:19] offset1:1
	v_add_u32_e32 v8, 0x1100, v121
	s_waitcnt vmcnt(11)
	ds_write2_b64 v8, v[28:29], v[30:31] offset1:1
	v_add_u32_e32 v8, 0x1540, v121
	s_waitcnt vmcnt(10)
	ds_write2_b64 v8, v[24:25], v[26:27] offset1:1
	v_add_u32_e32 v8, 0x1980, v121
	s_waitcnt vmcnt(9)
	ds_write2_b64 v8, v[36:37], v[38:39] offset1:1
	v_add_u32_e32 v8, 0x1dc0, v121
	s_waitcnt vmcnt(8)
	ds_write2_b64 v8, v[32:33], v[34:35] offset1:1
	v_add_u32_e32 v8, 0x2200, v121
	s_waitcnt vmcnt(7)
	ds_write2_b64 v8, v[44:45], v[46:47] offset1:1
	v_add_u32_e32 v8, 0x2640, v121
	s_waitcnt vmcnt(6)
	ds_write2_b64 v8, v[40:41], v[42:43] offset1:1
	v_add_u32_e32 v8, 0x2a80, v121
	s_waitcnt vmcnt(5)
	ds_write2_b64 v8, v[52:53], v[54:55] offset1:1
	v_add_u32_e32 v8, 0x2ec0, v121
	s_waitcnt vmcnt(4)
	ds_write2_b64 v8, v[48:49], v[50:51] offset1:1
	v_add_u32_e32 v8, 0x3300, v121
	s_waitcnt vmcnt(3)
	ds_write2_b64 v8, v[60:61], v[62:63] offset1:1
	v_add_u32_e32 v8, 0x3740, v121
	s_waitcnt vmcnt(2)
	ds_write2_b64 v8, v[56:57], v[58:59] offset1:1
	v_add_u32_e32 v8, 0x3b80, v121
	s_waitcnt vmcnt(1)
	ds_write2_b64 v8, v[68:69], v[70:71] offset1:1
	v_add_u32_e32 v8, 0x3fc0, v121
	s_waitcnt vmcnt(0)
	ds_write2_b64 v8, v[64:65], v[66:67] offset1:1
	v_add_u32_e32 v224, 0x880, v122
	v_add_u32_e32 v225, 0x1100, v122
	v_add_u32_e32 v226, 0x1980, v122
	v_add_u32_e32 v227, 0x2200, v122
	v_add_u32_e32 v228, 0x2a80, v122
	v_add_u32_e32 v229, 0x3300, v122
	v_add_u32_e32 v230, 0x3b80, v122
	ds_read2_b64 v[12:15], v122 offset1:1
	ds_read2_b64 v[20:23], v224 offset1:1
	ds_read2_b64 v[28:31], v225 offset1:1
	ds_read2_b64 v[36:39], v226 offset1:1
	ds_read2_b64 v[44:47], v227 offset1:1
	ds_read2_b64 v[52:55], v228 offset1:1
	ds_read2_b64 v[60:63], v229 offset1:1
	ds_read2_b64 v[68:71], v230 offset1:1
	ds_read2_b64 v[8:11], v122 offset0:8 offset1:9
	ds_read2_b64 v[16:19], v224 offset0:8 offset1:9
	ds_read2_b64 v[24:27], v225 offset0:8 offset1:9
	ds_read2_b64 v[32:35], v226 offset0:8 offset1:9
	ds_read2_b64 v[40:43], v227 offset0:8 offset1:9
	ds_read2_b64 v[48:51], v228 offset0:8 offset1:9
	ds_read2_b64 v[56:59], v229 offset0:8 offset1:9
	s_waitcnt lgkmcnt(14)
	ds_read2_b64 v[64:67], v230 offset0:8 offset1:9
	s_waitcnt lgkmcnt(8)
	v_mfma_scale_f32_16x16x128_f8f6f4 v[142:145], v[12:15], v[72:75], 0, v183, v183 op_sel_hi:[0,0,0] cbsz:4 blgp:4
	v_mfma_scale_f32_16x16x128_f8f6f4 v[146:149], v[20:23], v[72:75], 0, v183, v183 op_sel_hi:[0,0,0] cbsz:4 blgp:4
	v_mfma_scale_f32_16x16x128_f8f6f4 v[150:153], v[28:31], v[72:75], 0, v183, v183 op_sel_hi:[0,0,0] cbsz:4 blgp:4
	v_mfma_scale_f32_16x16x128_f8f6f4 v[154:157], v[36:39], v[72:75], 0, v183, v183 op_sel_hi:[0,0,0] cbsz:4 blgp:4
	v_mfma_scale_f32_16x16x128_f8f6f4 v[158:161], v[44:47], v[72:75], 0, v183, v183 op_sel_hi:[0,0,0] cbsz:4 blgp:4
	v_mfma_scale_f32_16x16x128_f8f6f4 v[162:165], v[52:55], v[72:75], 0, v183, v183 op_sel_hi:[0,0,0] cbsz:4 blgp:4
	v_mfma_scale_f32_16x16x128_f8f6f4 v[166:169], v[60:63], v[72:75], 0, v183, v183 op_sel_hi:[0,0,0] cbsz:4 blgp:4
	v_mfma_scale_f32_16x16x128_f8f6f4 v[170:173], v[68:71], v[72:75], 0, v183, v183 op_sel_hi:[0,0,0] cbsz:4 blgp:4
	v_mfma_scale_f32_16x16x128_f8f6f4 v[142:145], v[12:15], v[80:83], v[142:145], v183, v184 op_sel_hi:[0,0,0] cbsz:4 blgp:4
	v_mfma_scale_f32_16x16x128_f8f6f4 v[146:149], v[20:23], v[80:83], v[146:149], v183, v184 op_sel_hi:[0,0,0] cbsz:4 blgp:4
	v_mfma_scale_f32_16x16x128_f8f6f4 v[150:153], v[28:31], v[80:83], v[150:153], v183, v184 op_sel_hi:[0,0,0] cbsz:4 blgp:4
	v_mfma_scale_f32_16x16x128_f8f6f4 v[154:157], v[36:39], v[80:83], v[154:157], v183, v184 op_sel_hi:[0,0,0] cbsz:4 blgp:4
	v_mfma_scale_f32_16x16x128_f8f6f4 v[158:161], v[44:47], v[80:83], v[158:161], v183, v184 op_sel_hi:[0,0,0] cbsz:4 blgp:4
	v_mfma_scale_f32_16x16x128_f8f6f4 v[162:165], v[52:55], v[80:83], v[162:165], v183, v184 op_sel_hi:[0,0,0] cbsz:4 blgp:4
	v_mfma_scale_f32_16x16x128_f8f6f4 v[166:169], v[60:63], v[80:83], v[166:169], v183, v184 op_sel_hi:[0,0,0] cbsz:4 blgp:4
	v_mfma_scale_f32_16x16x128_f8f6f4 v[170:173], v[68:71], v[80:83], v[170:173], v183, v184 op_sel_hi:[0,0,0] cbsz:4 blgp:4
	s_waitcnt lgkmcnt(0)
	v_mfma_scale_f32_16x16x128_f8f6f4 v[142:145], v[8:11], v[4:7], v[142:145], v183, v183 op_sel_hi:[0,0,0] cbsz:4 blgp:4
	v_mfma_scale_f32_16x16x128_f8f6f4 v[146:149], v[16:19], v[4:7], v[146:149], v183, v183 op_sel_hi:[0,0,0] cbsz:4 blgp:4
	v_mfma_scale_f32_16x16x128_f8f6f4 v[150:153], v[24:27], v[4:7], v[150:153], v183, v183 op_sel_hi:[0,0,0] cbsz:4 blgp:4
	v_mfma_scale_f32_16x16x128_f8f6f4 v[154:157], v[32:35], v[4:7], v[154:157], v183, v183 op_sel_hi:[0,0,0] cbsz:4 blgp:4
	v_mfma_scale_f32_16x16x128_f8f6f4 v[158:161], v[40:43], v[4:7], v[158:161], v183, v183 op_sel_hi:[0,0,0] cbsz:4 blgp:4
	v_mfma_scale_f32_16x16x128_f8f6f4 v[162:165], v[48:51], v[4:7], v[162:165], v183, v183 op_sel_hi:[0,0,0] cbsz:4 blgp:4
	v_mfma_scale_f32_16x16x128_f8f6f4 v[166:169], v[56:59], v[4:7], v[166:169], v183, v183 op_sel_hi:[0,0,0] cbsz:4 blgp:4
	v_mfma_scale_f32_16x16x128_f8f6f4 v[170:173], v[64:67], v[4:7], v[170:173], v183, v183 op_sel_hi:[0,0,0] cbsz:4 blgp:4
	v_mfma_scale_f32_16x16x128_f8f6f4 v[142:145], v[8:11], v[76:79], v[142:145], v183, v184 op_sel_hi:[0,0,0] cbsz:4 blgp:4
	v_mfma_scale_f32_16x16x128_f8f6f4 v[146:149], v[16:19], v[76:79], v[146:149], v183, v184 op_sel_hi:[0,0,0] cbsz:4 blgp:4
	v_mfma_scale_f32_16x16x128_f8f6f4 v[150:153], v[24:27], v[76:79], v[150:153], v183, v184 op_sel_hi:[0,0,0] cbsz:4 blgp:4
	v_mfma_scale_f32_16x16x128_f8f6f4 v[154:157], v[32:35], v[76:79], v[154:157], v183, v184 op_sel_hi:[0,0,0] cbsz:4 blgp:4
	v_mfma_scale_f32_16x16x128_f8f6f4 v[158:161], v[40:43], v[76:79], v[158:161], v183, v184 op_sel_hi:[0,0,0] cbsz:4 blgp:4
	v_mfma_scale_f32_16x16x128_f8f6f4 v[162:165], v[48:51], v[76:79], v[162:165], v183, v184 op_sel_hi:[0,0,0] cbsz:4 blgp:4
	v_mfma_scale_f32_16x16x128_f8f6f4 v[166:169], v[56:59], v[76:79], v[166:169], v183, v184 op_sel_hi:[0,0,0] cbsz:4 blgp:4
	v_mfma_scale_f32_16x16x128_f8f6f4 v[170:173], v[64:67], v[76:79], v[170:173], v183, v184 op_sel_hi:[0,0,0] cbsz:4 blgp:4
	s_and_saveexec_b64 s[78:79], s[48:49]
	s_nop 0
	ds_write_b128 v118, v[142:145] offset:17920
	ds_write_b128 v118, v[146:149] offset:17984
	ds_write_b128 v118, v[150:153] offset:18048
	ds_write_b128 v118, v[154:157] offset:18112
	ds_write_b128 v118, v[158:161] offset:18176
	ds_write_b128 v118, v[162:165] offset:18240
	ds_write_b128 v118, v[166:169] offset:18304
	s_nop 1
	ds_write_b128 v118, v[170:173] offset:18368
	s_or_b64 exec, exec, s[78:79]
	ds_read2st64_b32 v[4:5], v85 offset0:70 offset1:71
	s_andn2_b64 vcc, exec, s[74:75]
	s_waitcnt lgkmcnt(0)
	v_pk_fma_f32 v[4:5], v[4:5], 0.5, v[114:115] op_sel_hi:[1,0,1]
	s_cbranch_vccnz .LBB0_1085
	s_mov_b32 s30, 0x3c800000
	v_pk_mul_f32 v[4:5], v[4:5], s[30:31] op_sel_hi:[1,0]
	s_mov_b32 s30, 0x3d9d89d9
	v_mul_f32_e32 v6, 0x3d372713, v4
	v_mul_f32_e32 v7, 0x3d372713, v5
	v_mul_f32_e32 v6, v4, v6
	v_mul_f32_e32 v7, v5, v7
	v_fma_f32 v6, v4, v6, v4
	v_fma_f32 v7, v5, v7, v5
	v_mul_f32_e32 v6, 0x3f4c422a, v6
	v_mul_f32_e32 v7, 0x3f4c422a, v7
	v_mul_f32_e32 v6, -2.0, v6
	v_mul_f32_e32 v7, -2.0, v7
	v_mul_f32_e32 v6, 0x3fb8aa3b, v6
	v_mul_f32_e32 v7, 0x3fb8aa3b, v7
	v_exp_f32_e32 v6, v6
	v_exp_f32_e32 v7, v7
	s_nop 0
	v_pk_add_f32 v[6:7], v[6:7], 1.0 op_sel_hi:[1,0]
	s_nop 0
	v_div_scale_f32 v8, s[38:39], v7, v7, v5
	v_rcp_f32_e32 v9, v8
	s_nop 0
	v_fma_f32 v10, -v8, v9, 1.0
	v_fmac_f32_e32 v9, v10, v9
	v_div_scale_f32 v10, vcc, v5, v7, v5
	v_mul_f32_e32 v11, v10, v9
	v_fma_f32 v12, -v8, v11, v10
	v_fmac_f32_e32 v11, v12, v9
	v_fma_f32 v8, -v8, v11, v10
	v_div_fmas_f32 v8, v8, v9, v11
	v_div_fixup_f32 v5, v8, v7, v5
	v_div_scale_f32 v7, s[38:39], v6, v6, v4
	v_rcp_f32_e32 v8, v7
	s_nop 0
	v_fma_f32 v9, -v7, v8, 1.0
	v_fmac_f32_e32 v8, v9, v8
	v_div_scale_f32 v9, vcc, v4, v6, v4
	v_mul_f32_e32 v10, v9, v8
	v_fma_f32 v11, -v7, v10, v9
	v_fmac_f32_e32 v10, v11, v8
	v_fma_f32 v7, -v7, v10, v9
	v_div_fmas_f32 v7, v7, v8, v10
	v_div_fixup_f32 v4, v7, v6, v4
	v_pk_mul_f32 v[4:5], v[106:107], v[4:5]
	s_nop 0
	v_pk_mul_f32 v[4:5], v[4:5], s[30:31] op_sel_hi:[1,0]
	s_branch .LBB0_1085
